# experiment: remove the per-burst s_setprio 1/0 pairs in the 4 nsa_wg instances
# baseline (speedup 1.0000x reference)
.LBB0_2309:
	s_or_b32 s51, s52, s16
	s_lshl_b32 s53, s51, 4
	s_cmp_ge_i32 s53, s24
	s_cbranch_scc1 .LBB0_2308
	v_or_b32_e32 v49, s52, v226
	v_mad_u32_u24 v49, v49, s48, v44
	ds_read_b128 v[50:53], v49
	ds_read_b128 v[54:57], v49 offset:64
	ds_read_b128 v[58:61], v49 offset:2304
	ds_read_b128 v[62:65], v49 offset:2368
	v_subrev_u32_e32 v49, s51, v1
	v_lshl_add_u32 v49, v49, 4, v161
	v_cvt_f32_u32_e32 v66, v49
	v_xad_u32 v67, s51, -1, v1
	v_lshl_add_u32 v67, v67, 4, v161
	v_cvt_f32_u32_e32 v68, v67
	v_cmp_gt_u32_e32 vcc, 2.0, v49
	s_nop 1
	v_cndmask_b32_e32 v49, v48, v66, vcc
	v_subrev_u32_e32 v66, s51, v162
	v_cmp_gt_u32_e32 vcc, 2.0, v67
	v_lshl_add_u32 v66, v66, 4, v161
	v_cvt_f32_u32_e32 v67, v66
	v_cndmask_b32_e32 v90, v48, v68, vcc
	v_subrev_u32_e32 v68, s51, v163
	v_lshl_add_u32 v68, v68, 4, v161
	v_cvt_f32_u32_e32 v69, v68
	v_cmp_gt_u32_e32 vcc, 2.0, v66
	v_subrev_u32_e32 v66, s51, v164
	v_lshl_add_u32 v66, v66, 4, v161
	v_cndmask_b32_e32 v91, v48, v67, vcc
	v_cmp_gt_u32_e32 vcc, 2.0, v68
	v_cvt_f32_u32_e32 v67, v66
	v_subrev_u32_e32 v68, s51, v165
	v_lshl_add_u32 v68, v68, 4, v161
	v_cndmask_b32_e32 v92, v48, v69, vcc
	v_cvt_f32_u32_e32 v69, v68
	v_cmp_gt_u32_e32 vcc, 2.0, v66
	v_subrev_u32_e32 v66, s51, v166
	v_lshl_add_u32 v66, v66, 4, v161
	v_cndmask_b32_e32 v93, v48, v67, vcc
	v_cmp_gt_u32_e32 vcc, 2.0, v68
	v_subrev_u32_e32 v68, s51, v167
	v_cvt_f32_u32_e32 v67, v66
	v_lshl_add_u32 v68, v68, 4, v161
	v_cndmask_b32_e32 v94, v48, v69, vcc
	v_cvt_f32_u32_e32 v69, v68
	v_cmp_gt_u32_e32 vcc, 2.0, v66
	s_nop 1
	v_cndmask_b32_e32 v95, v48, v67, vcc
	v_cmp_gt_u32_e32 vcc, 2.0, v68
	s_nop 1
	v_cndmask_b32_e32 v96, v48, v69, vcc
	s_waitcnt lgkmcnt(3)
	v_mfma_f32_16x16x32_bf16 v[66:69], v[50:53], v[2:5], 0
	v_mfma_f32_16x16x32_bf16 v[74:77], v[50:53], v[10:13], 0
	v_mfma_f32_16x16x32_bf16 v[82:85], v[50:53], v[18:21], 0
	v_mfma_f32_16x16x32_bf16 v[50:53], v[50:53], v[26:29], 0
	s_waitcnt lgkmcnt(2)
	v_mfma_f32_16x16x32_bf16 v[66:69], v[54:57], v[6:9], v[66:69]
	s_waitcnt lgkmcnt(1)
	v_mfma_f32_16x16x32_bf16 v[70:73], v[58:61], v[2:5], 0
	v_mfma_f32_16x16x32_bf16 v[74:77], v[54:57], v[14:17], v[74:77]
	v_mfma_f32_16x16x32_bf16 v[78:81], v[58:61], v[10:13], 0
	v_mfma_f32_16x16x32_bf16 v[82:85], v[54:57], v[22:25], v[82:85]
	v_mfma_f32_16x16x32_bf16 v[86:89], v[58:61], v[18:21], 0
	v_mfma_f32_16x16x32_bf16 v[50:53], v[54:57], v[30:33], v[50:53]
	v_mfma_f32_16x16x32_bf16 v[54:57], v[58:61], v[26:29], 0
	s_waitcnt lgkmcnt(0)
	v_mfma_f32_16x16x32_bf16 v[70:73], v[62:65], v[6:9], v[70:73]
	v_mfma_f32_16x16x32_bf16 v[78:81], v[62:65], v[14:17], v[78:81]
	v_mfma_f32_16x16x32_bf16 v[86:89], v[62:65], v[22:25], v[86:89]
	v_mfma_f32_16x16x32_bf16 v[54:57], v[62:65], v[30:33], v[54:57]
	v_fma_f32 v58, -v215, v49, v66
	v_exp_f32_e32 v59, v58
	v_fma_f32 v58, -v215, v90, v67
	v_exp_f32_e32 v61, v58
	v_fma_f32 v58, -v215, v91, v68
	v_exp_f32_e32 v63, v58
	v_fma_f32 v58, -v215, v92, v69
	v_exp_f32_e32 v65, v58
	v_fma_f32 v58, -v215, v93, v70
	v_exp_f32_e32 v67, v58
	v_fma_f32 v58, -v215, v94, v71
	v_exp_f32_e32 v69, v58
	v_fma_f32 v58, -v215, v95, v72
	v_exp_f32_e32 v71, v58
	v_fma_f32 v58, -v215, v96, v73
	v_exp_f32_e32 v73, v58
	v_fma_f32 v58, -v216, v49, v74
	v_exp_f32_e32 v58, v58
	v_fma_f32 v60, -v216, v90, v75
	v_exp_f32_e32 v60, v60
	v_fma_f32 v62, -v216, v91, v76
	v_exp_f32_e32 v62, v62
	v_fma_f32 v64, -v216, v92, v77
	v_exp_f32_e32 v64, v64
	v_fma_f32 v66, -v216, v93, v78
	v_exp_f32_e32 v66, v66
	v_fma_f32 v68, -v216, v94, v79
	v_pk_add_f32 v[58:59], v[58:59], 0 op_sel_hi:[1,0]
	v_exp_f32_e32 v68, v68
	v_fma_f32 v70, -v216, v95, v80
	v_pk_add_f32 v[58:59], v[60:61], v[58:59]
	v_exp_f32_e32 v70, v70
	v_fma_f32 v72, -v216, v96, v81
	v_pk_add_f32 v[58:59], v[62:63], v[58:59]
	v_exp_f32_e32 v72, v72
	v_pk_add_f32 v[58:59], v[64:65], v[58:59]
	s_nop 0
	v_pk_add_f32 v[58:59], v[66:67], v[58:59]
	s_nop 0
	v_pk_add_f32 v[58:59], v[68:69], v[58:59]
	s_nop 0
	v_pk_add_f32 v[58:59], v[70:71], v[58:59]
	s_nop 0
	v_pk_add_f32 v[58:59], v[72:73], v[58:59]
	s_nop 0
	v_pk_add_f32 v[46:47], v[46:47], v[58:59]
	v_fma_f32 v58, -v217, v49, v82
	v_exp_f32_e32 v59, v58
	v_fma_f32 v58, -v217, v90, v83
	v_exp_f32_e32 v61, v58
	v_fma_f32 v58, -v217, v91, v84
	v_exp_f32_e32 v63, v58
	v_fma_f32 v58, -v217, v92, v85
	v_exp_f32_e32 v65, v58
	v_fma_f32 v58, -v217, v93, v86
	v_exp_f32_e32 v67, v58
	v_fma_f32 v58, -v217, v94, v87
	v_exp_f32_e32 v69, v58
	v_fma_f32 v58, -v217, v95, v88
	v_exp_f32_e32 v71, v58
	v_fma_f32 v58, -v217, v96, v89
	v_fma_f32 v49, -v218, v49, v50
	v_exp_f32_e32 v73, v58
	v_exp_f32_e32 v58, v49
	v_fma_f32 v49, -v218, v90, v51
	v_exp_f32_e32 v60, v49
	v_fma_f32 v49, -v218, v91, v52
	v_exp_f32_e32 v62, v49
	v_fma_f32 v49, -v218, v92, v53
	v_exp_f32_e32 v64, v49
	v_fma_f32 v49, -v218, v93, v54
	v_exp_f32_e32 v66, v49
	v_fma_f32 v49, -v218, v94, v55
	v_pk_add_f32 v[50:51], v[58:59], 0 op_sel_hi:[1,0]
	v_exp_f32_e32 v68, v49
	v_fma_f32 v49, -v218, v95, v56
	v_pk_add_f32 v[50:51], v[60:61], v[50:51]
	v_exp_f32_e32 v70, v49
	v_fma_f32 v49, -v218, v96, v57
	v_pk_add_f32 v[50:51], v[62:63], v[50:51]
	v_exp_f32_e32 v72, v49
	v_pk_add_f32 v[50:51], v[64:65], v[50:51]
	s_nop 0
	v_pk_add_f32 v[50:51], v[66:67], v[50:51]
	s_nop 0
	v_pk_add_f32 v[50:51], v[68:69], v[50:51]
	s_nop 0
	v_pk_add_f32 v[50:51], v[70:71], v[50:51]
	s_nop 0
	v_pk_add_f32 v[50:51], v[72:73], v[50:51]
	s_nop 0
	v_pk_add_f32 v[42:43], v[42:43], v[50:51]
	s_branch .LBB0_2308

.LBB0_2320:
	s_lshl_b32 s52, s51, 5
	s_or_b32 s50, s52, s49
	s_lshl_b32 s53, s50, 4
	s_cmp_ge_i32 s53, s24
	s_cbranch_scc1 .LBB0_2319
	v_subrev_u32_e32 v171, s50, v1
	v_lshl_add_u32 v171, v171, 4, v161
	v_cvt_f32_u32_e32 v188, v171
	v_xad_u32 v189, s50, -1, v1
	v_lshl_add_u32 v189, v189, 4, v161
	v_cvt_f32_u32_e32 v190, v189
	v_cmp_gt_u32_e32 vcc, 2.0, v171
	v_or_b32_e32 v108, s52, v226
	v_mad_u32_u24 v108, v108, s20, v98
	v_cndmask_b32_e32 v171, v169, v188, vcc
	v_subrev_u32_e32 v188, s50, v162
	v_cmp_gt_u32_e32 vcc, 2.0, v189
	v_lshl_add_u32 v188, v188, 4, v161
	v_cvt_f32_u32_e32 v189, v188
	v_cndmask_b32_e32 v212, v169, v190, vcc
	v_subrev_u32_e32 v190, s50, v163
	v_lshl_add_u32 v190, v190, 4, v161
	v_cvt_f32_u32_e32 v191, v190
	v_cmp_gt_u32_e32 vcc, 2.0, v188
	v_subrev_u32_e32 v188, s50, v164
	v_lshl_add_u32 v188, v188, 4, v161
	v_cndmask_b32_e32 v213, v169, v189, vcc
	v_cmp_gt_u32_e32 vcc, 2.0, v190
	v_cvt_f32_u32_e32 v189, v188
	v_subrev_u32_e32 v190, s50, v165
	v_lshl_add_u32 v190, v190, 4, v161
	v_lshl_add_u32 v120, s51, 6, v170
	v_cndmask_b32_e32 v224, v169, v191, vcc
	v_cvt_f32_u32_e32 v191, v190
	ds_read_b128 v[172:175], v108
	ds_read_b128 v[176:179], v108 offset:64
	ds_read_b128 v[180:183], v108 offset:2304
	ds_read_b128 v[184:187], v108 offset:2368
	ds_read_b128 v[108:111], v120 offset:9216
	ds_read_b128 v[112:115], v120 offset:11520
	ds_read_b128 v[116:119], v120 offset:13824
	ds_read_b128 v[120:123], v120 offset:16128
	v_cmp_gt_u32_e32 vcc, 2.0, v188
	v_subrev_u32_e32 v188, s50, v166
	v_lshl_add_u32 v188, v188, 4, v161
	v_cndmask_b32_e32 v225, v169, v189, vcc
	v_cmp_gt_u32_e32 vcc, 2.0, v190
	v_subrev_u32_e32 v190, s50, v167
	v_cvt_f32_u32_e32 v189, v188
	v_lshl_add_u32 v190, v190, 4, v161
	v_cndmask_b32_e32 v232, v169, v191, vcc
	v_cvt_f32_u32_e32 v191, v190
	v_cmp_gt_u32_e32 vcc, 2.0, v188
	s_nop 1
	v_cndmask_b32_e32 v233, v169, v189, vcc
	v_cmp_gt_u32_e32 vcc, 2.0, v190
	s_nop 1
	v_cndmask_b32_e32 v234, v169, v191, vcc
	s_waitcnt lgkmcnt(7)
	v_mfma_f32_16x16x32_bf16 v[188:191], v[172:175], v[2:5], 0
	v_mfma_f32_16x16x32_bf16 v[196:199], v[172:175], v[10:13], 0
	v_mfma_f32_16x16x32_bf16 v[204:207], v[172:175], v[18:21], 0
	v_mfma_f32_16x16x32_bf16 v[172:175], v[172:175], v[26:29], 0
	s_waitcnt lgkmcnt(6)
	v_mfma_f32_16x16x32_bf16 v[188:191], v[176:179], v[6:9], v[188:191]
	s_waitcnt lgkmcnt(5)
	v_mfma_f32_16x16x32_bf16 v[192:195], v[180:183], v[2:5], 0
	v_mfma_f32_16x16x32_bf16 v[196:199], v[176:179], v[14:17], v[196:199]
	v_mfma_f32_16x16x32_bf16 v[200:203], v[180:183], v[10:13], 0
	v_mfma_f32_16x16x32_bf16 v[204:207], v[176:179], v[22:25], v[204:207]
	v_mfma_f32_16x16x32_bf16 v[208:211], v[180:183], v[18:21], 0
	v_mfma_f32_16x16x32_bf16 v[172:175], v[176:179], v[30:33], v[172:175]
	v_mfma_f32_16x16x32_bf16 v[176:179], v[180:183], v[26:29], 0
	s_waitcnt lgkmcnt(4)
	v_mfma_f32_16x16x32_bf16 v[192:195], v[184:187], v[6:9], v[192:195]
	v_mfma_f32_16x16x32_bf16 v[200:203], v[184:187], v[14:17], v[200:203]
	v_mfma_f32_16x16x32_bf16 v[208:211], v[184:187], v[22:25], v[208:211]
	v_mfma_f32_16x16x32_bf16 v[176:179], v[184:187], v[30:33], v[176:179]
	v_fma_f32 v180, -v215, v171, v188
	v_fma_f32 v181, -v215, v212, v189
	v_fma_f32 v182, -v215, v213, v190
	v_fma_f32 v183, -v215, v224, v191
	v_exp_f32_e32 v180, v180
	v_exp_f32_e32 v181, v181
	v_exp_f32_e32 v182, v182
	v_exp_f32_e32 v183, v183
	v_fma_f32 v184, -v215, v225, v192
	v_fma_f32 v185, -v215, v232, v193
	v_fma_f32 v186, -v215, v233, v194
	v_fma_f32 v187, -v215, v234, v195
	v_exp_f32_e32 v184, v184
	v_exp_f32_e32 v185, v185
	v_exp_f32_e32 v186, v186
	v_exp_f32_e32 v187, v187
	v_pk_mul_f32 v[180:181], v[150:151], v[180:181]
	v_pk_mul_f32 v[182:183], v[150:151], v[182:183]
	v_add_f32_e32 v189, v180, v181
	v_add_f32_e32 v188, v182, v183
	v_pk_mul_f32 v[184:185], v[150:151], v[184:185]
	v_pk_mul_f32 v[186:187], v[150:151], v[186:187]
	v_add_f32_e32 v188, v189, v188
	v_add_f32_e32 v192, 0, v188
	v_add_f32_e32 v188, v186, v187
	v_add_f32_e32 v189, v184, v185
	v_add_f32_e32 v193, 0, v183
	v_add_f32_e32 v188, v189, v188
	v_add_f32_e32 v195, 0, v187
	v_cvt_pk_bf16_f32 v180, v180, v181
	v_cvt_pk_bf16_f32 v181, v182, v183
	v_cvt_pk_bf16_f32 v182, v184, v185
	v_cvt_pk_bf16_f32 v183, v186, v187
	v_fma_f32 v184, -v216, v171, v196
	v_fma_f32 v185, -v216, v212, v197
	v_fma_f32 v186, -v216, v213, v198
	v_fma_f32 v187, -v216, v224, v199
	v_add_f32_e32 v194, 0, v188
	v_exp_f32_e32 v184, v184
	v_exp_f32_e32 v185, v185
	v_exp_f32_e32 v186, v186
	v_exp_f32_e32 v187, v187
	v_fma_f32 v188, -v216, v225, v200
	v_fma_f32 v189, -v216, v232, v201
	v_exp_f32_e32 v188, v188
	v_exp_f32_e32 v189, v189
	v_fma_f32 v190, -v216, v233, v202
	v_fma_f32 v191, -v216, v234, v203
	v_pk_mul_f32 v[184:185], v[152:153], v[184:185]
	v_pk_mul_f32 v[186:187], v[152:153], v[186:187]
	v_exp_f32_e32 v190, v190
	v_exp_f32_e32 v191, v191
	v_pk_mul_f32 v[188:189], v[152:153], v[188:189]
	v_add_f32_e32 v196, v186, v187
	v_add_f32_e32 v197, v184, v185
	v_add_f32_e32 v196, v197, v196
	v_add_f32_e32 v197, v193, v187
	v_add_f32_e32 v193, v188, v189
	v_cvt_pk_bf16_f32 v184, v184, v185
	v_cvt_pk_bf16_f32 v185, v186, v187
	v_cvt_pk_bf16_f32 v186, v188, v189
	v_fma_f32 v188, -v217, v171, v204
	v_fma_f32 v171, -v218, v171, v172
	v_exp_f32_e32 v172, v171
	v_fma_f32 v171, -v218, v212, v173
	v_exp_f32_e32 v173, v171
	v_fma_f32 v171, -v218, v213, v174
	v_pk_mul_f32 v[190:191], v[152:153], v[190:191]
	v_exp_f32_e32 v174, v171
	v_fma_f32 v171, -v218, v224, v175
	v_add_f32_e32 v196, v192, v196
	v_add_f32_e32 v192, v190, v191
	v_add_f32_e32 v199, v195, v191
	v_cvt_pk_bf16_f32 v187, v190, v191
	v_fma_f32 v189, -v217, v212, v205
	v_fma_f32 v190, -v217, v213, v206
	v_fma_f32 v191, -v217, v224, v207
	v_exp_f32_e32 v175, v171
	v_fma_f32 v171, -v218, v225, v176
	v_add_f32_e32 v192, v193, v192
	v_exp_f32_e32 v188, v188
	v_exp_f32_e32 v189, v189
	v_exp_f32_e32 v190, v190
	v_exp_f32_e32 v191, v191
	v_exp_f32_e32 v176, v171
	v_fma_f32 v171, -v218, v232, v177
	v_add_f32_e32 v198, v194, v192
	v_fma_f32 v192, -v217, v225, v208
	v_fma_f32 v193, -v217, v232, v209
	v_fma_f32 v194, -v217, v233, v210
	v_fma_f32 v195, -v217, v234, v211
	v_exp_f32_e32 v177, v171
	v_fma_f32 v171, -v218, v233, v178
	v_exp_f32_e32 v192, v192
	v_exp_f32_e32 v193, v193
	v_exp_f32_e32 v194, v194
	v_exp_f32_e32 v195, v195
	v_exp_f32_e32 v178, v171
	v_fma_f32 v171, -v218, v234, v179
	v_exp_f32_e32 v179, v171
	v_pk_mul_f32 v[188:189], v[154:155], v[188:189]
	v_pk_mul_f32 v[190:191], v[154:155], v[190:191]
	v_add_f32_e32 v201, v188, v189
	v_add_f32_e32 v200, v190, v191
	v_pk_mul_f32 v[192:193], v[154:155], v[192:193]
	v_pk_mul_f32 v[194:195], v[154:155], v[194:195]
	v_add_f32_e32 v200, v201, v200
	v_add_f32_e32 v196, v196, v200
	v_add_f32_e32 v200, v194, v195
	v_add_f32_e32 v201, v192, v193
	v_pk_mul_f32 v[172:173], v[156:157], v[172:173]
	v_pk_mul_f32 v[174:175], v[156:157], v[174:175]
	v_pk_mul_f32 v[176:177], v[156:157], v[176:177]
	v_pk_mul_f32 v[178:179], v[156:157], v[178:179]
	v_add_f32_e32 v197, v197, v191
	v_add_f32_e32 v200, v201, v200
	v_cvt_pk_bf16_f32 v188, v188, v189
	v_cvt_pk_bf16_f32 v189, v190, v191
	v_cvt_pk_bf16_f32 v190, v192, v193
	v_cvt_pk_bf16_f32 v191, v194, v195
	v_add_f32_e32 v171, v174, v175
	v_add_f32_e32 v192, v172, v173
	v_add_f32_e32 v193, v178, v179
	v_add_f32_e32 v194, v176, v177
	v_add_f32_e32 v198, v198, v200
	v_add_f32_e32 v199, v199, v195
	v_add_f32_e32 v171, v192, v171
	v_add_f32_e32 v193, v194, v193
	v_add_f32_e32 v171, v196, v171
	v_add_f32_e32 v192, v197, v175
	v_add_f32_e32 v193, v198, v193
	v_add_f32_e32 v194, v199, v179
	v_cvt_pk_bf16_f32 v172, v172, v173
	v_cvt_pk_bf16_f32 v173, v174, v175
	v_cvt_pk_bf16_f32 v174, v176, v177
	v_cvt_pk_bf16_f32 v175, v178, v179
	s_waitcnt lgkmcnt(3)
	v_mfma_f32_16x16x32_bf16 v[94:97], v[108:111], v[180:183], v[94:97]
	s_waitcnt lgkmcnt(2)
	v_mfma_f32_16x16x32_bf16 v[90:93], v[112:115], v[180:183], v[90:93]
	s_waitcnt lgkmcnt(1)
	v_mfma_f32_16x16x32_bf16 v[86:89], v[116:119], v[180:183], v[86:89]
	s_waitcnt lgkmcnt(0)
	v_mfma_f32_16x16x32_bf16 v[82:85], v[120:123], v[180:183], v[82:85]
	v_mfma_f32_16x16x32_bf16 v[78:81], v[108:111], v[184:187], v[78:81]
	v_mfma_f32_16x16x32_bf16 v[74:77], v[112:115], v[184:187], v[74:77]
	v_mfma_f32_16x16x32_bf16 v[70:73], v[116:119], v[184:187], v[70:73]
	v_mfma_f32_16x16x32_bf16 v[66:69], v[120:123], v[184:187], v[66:69]
	v_mfma_f32_16x16x32_bf16 v[62:65], v[108:111], v[188:191], v[62:65]
	v_mfma_f32_16x16x32_bf16 v[58:61], v[112:115], v[188:191], v[58:61]
	v_mfma_f32_16x16x32_bf16 v[54:57], v[116:119], v[188:191], v[54:57]
	v_mfma_f32_16x16x32_bf16 v[50:53], v[120:123], v[188:191], v[50:53]
	v_mfma_f32_16x16x32_bf16 v[46:49], v[108:111], v[172:175], v[46:49]
	v_mfma_f32_16x16x32_bf16 v[42:45], v[112:115], v[172:175], v[42:45]
	v_mfma_f32_16x16x32_bf16 v[38:41], v[116:119], v[172:175], v[38:41]
	v_mfma_f32_16x16x32_bf16 v[34:37], v[120:123], v[172:175], v[34:37]
	v_add_u32_e32 v108, s50, v168
	ds_add_f32 v108, v171
	ds_add_f32 v108, v192 offset:4
	ds_add_f32 v108, v193 offset:4
	ds_add_f32 v108, v194 offset:8
	s_branch .LBB0_2319

.LBB0_2477:
	s_lshl_b32 s21, s20, 5
	v_or_b32_e32 v151, s21, v226
	v_mad_u32_u24 v151, v151, s52, v148
	ds_read_b128 v[152:155], v151
	ds_read_b128 v[156:159], v151 offset:64
	ds_read_b128 v[160:163], v151 offset:2304
	ds_read_b128 v[164:167], v151 offset:2368
	v_lshl_add_u32 v151, s20, 6, v149
	ds_read_b128 v[168:171], v151 offset:9216
	ds_read_b128 v[172:175], v151 offset:11520
	ds_read_b128 v[176:179], v151 offset:13824
	ds_read_b128 v[182:185], v151 offset:16128
	v_add_u32_e32 v151, s21, v150
	v_sub_u32_e32 v180, v227, v151
	v_cmp_gt_u32_e32 vcc, 2.0, v180
	v_cvt_f32_i32_e32 v180, v180
	v_xad_u32 v186, v151, -1, v227
	v_cvt_f32_i32_e32 v187, v186
	s_and_b64 vcc, s[16:17], vcc
	v_cndmask_b32_e32 v180, v235, v180, vcc
	v_cmp_gt_u32_e32 vcc, 2.0, v186
	v_or_b32_e32 v186, 2, v151
	s_and_b64 vcc, s[16:17], vcc
	v_sub_u32_e32 v186, v227, v186
	v_cndmask_b32_e32 v236, v235, v187, vcc
	v_cmp_gt_u32_e32 vcc, 2.0, v186
	v_cvt_f32_i32_e32 v186, v186
	v_or_b32_e32 v187, 3, v151
	v_sub_u32_e32 v187, v227, v187
	v_cvt_f32_i32_e32 v188, v187
	s_and_b64 vcc, s[16:17], vcc
	v_cndmask_b32_e32 v237, v235, v186, vcc
	v_cmp_gt_u32_e32 vcc, 2.0, v187
	v_or_b32_e32 v186, 4, v151
	s_and_b64 vcc, s[16:17], vcc
	v_sub_u32_e32 v186, v227, v186
	v_cndmask_b32_e32 v238, v235, v188, vcc
	v_cmp_gt_u32_e32 vcc, 2.0, v186
	v_cvt_f32_i32_e32 v186, v186
	v_or_b32_e32 v187, 5, v151
	v_sub_u32_e32 v187, v227, v187
	v_cvt_f32_i32_e32 v188, v187
	s_and_b64 vcc, s[16:17], vcc
	v_cndmask_b32_e32 v239, v235, v186, vcc
	v_cmp_gt_u32_e32 vcc, 2.0, v187
	v_or_b32_e32 v186, 6, v151
	s_and_b64 vcc, s[16:17], vcc
	v_sub_u32_e32 v186, v227, v186
	v_cndmask_b32_e32 v240, v235, v188, vcc
	v_cmp_gt_u32_e32 vcc, 2.0, v186
	v_cvt_f32_i32_e32 v186, v186
	v_or_b32_e32 v151, 7, v151
	v_sub_u32_e32 v151, v227, v151
	v_cvt_f32_i32_e32 v187, v151
	s_and_b64 vcc, s[16:17], vcc
	v_cndmask_b32_e32 v241, v235, v186, vcc
	v_cmp_gt_u32_e32 vcc, 2.0, v151
	s_and_b64 vcc, s[16:17], vcc
	s_nop 0
	v_cndmask_b32_e32 v151, v235, v187, vcc
	s_waitcnt lgkmcnt(7)
	v_mfma_f32_16x16x32_bf16 v[186:189], v[152:155], v[2:5], 0
	v_mfma_f32_16x16x32_bf16 v[194:197], v[152:155], v[10:13], 0
	v_mfma_f32_16x16x32_bf16 v[202:205], v[152:155], v[18:21], 0
	v_mfma_f32_16x16x32_bf16 v[152:155], v[152:155], v[26:29], 0
	s_waitcnt lgkmcnt(6)
	v_mfma_f32_16x16x32_bf16 v[186:189], v[156:159], v[6:9], v[186:189]
	s_waitcnt lgkmcnt(5)
	v_mfma_f32_16x16x32_bf16 v[190:193], v[160:163], v[2:5], 0
	v_mfma_f32_16x16x32_bf16 v[194:197], v[156:159], v[14:17], v[194:197]
	v_mfma_f32_16x16x32_bf16 v[198:201], v[160:163], v[10:13], 0
	v_mfma_f32_16x16x32_bf16 v[202:205], v[156:159], v[22:25], v[202:205]
	v_mfma_f32_16x16x32_bf16 v[206:209], v[160:163], v[18:21], 0
	v_mfma_f32_16x16x32_bf16 v[152:155], v[156:159], v[30:33], v[152:155]
	v_mfma_f32_16x16x32_bf16 v[156:159], v[160:163], v[26:29], 0
	s_waitcnt lgkmcnt(4)
	v_mfma_f32_16x16x32_bf16 v[190:193], v[164:167], v[6:9], v[190:193]
	v_mfma_f32_16x16x32_bf16 v[198:201], v[164:167], v[14:17], v[198:201]
	v_mfma_f32_16x16x32_bf16 v[206:209], v[164:167], v[22:25], v[206:209]
	v_mfma_f32_16x16x32_bf16 v[156:159], v[164:167], v[30:33], v[156:159]
	v_fma_f32 v160, -v215, v180, v186
	v_fma_f32 v164, -v216, v180, v194
	v_exp_f32_e32 v165, v160
	v_fma_f32 v160, -v215, v236, v187
	v_exp_f32_e32 v164, v164
	v_fma_f32 v166, -v216, v236, v195
	v_exp_f32_e32 v167, v160
	v_fma_f32 v160, -v215, v237, v188
	v_exp_f32_e32 v166, v166
	v_fma_f32 v186, -v216, v237, v196
	v_exp_f32_e32 v187, v160
	v_fma_f32 v160, -v215, v238, v189
	v_exp_f32_e32 v186, v186
	v_fma_f32 v188, -v216, v238, v197
	v_exp_f32_e32 v189, v160
	v_fma_f32 v160, -v215, v239, v190
	v_exp_f32_e32 v188, v188
	v_fma_f32 v190, -v216, v239, v198
	v_exp_f32_e32 v211, v160
	v_fma_f32 v160, -v215, v240, v191
	v_exp_f32_e32 v210, v190
	v_fma_f32 v190, -v216, v240, v199
	v_pk_add_f32 v[194:195], v[164:165], 0 op_sel_hi:[1,0]
	v_exp_f32_e32 v191, v160
	v_fma_f32 v160, -v215, v241, v192
	v_exp_f32_e32 v190, v190
	v_fma_f32 v192, -v216, v241, v200
	v_pk_add_f32 v[194:195], v[166:167], v[194:195]
	v_exp_f32_e32 v213, v160
	v_fma_f32 v160, -v215, v151, v193
	v_exp_f32_e32 v212, v192
	v_fma_f32 v192, -v216, v151, v201
	v_pk_add_f32 v[194:195], v[186:187], v[194:195]
	v_exp_f32_e32 v193, v160
	v_exp_f32_e32 v192, v192
	v_pk_add_f32 v[194:195], v[188:189], v[194:195]
	v_fma_f32 v152, -v218, v180, v152
	v_pk_add_f32 v[194:195], v[210:211], v[194:195]
	v_cvt_pk_bf16_f32 v164, v164, v166
	v_pk_add_f32 v[194:195], v[190:191], v[194:195]
	v_cvt_pk_bf16_f32 v166, v210, v190
	v_pk_add_f32 v[194:195], v[212:213], v[194:195]
	v_exp_f32_e32 v190, v152
	v_fma_f32 v152, -v218, v236, v153
	v_cvt_pk_bf16_f32 v160, v165, v167
	v_pk_add_f32 v[194:195], v[192:193], v[194:195]
	v_cvt_pk_bf16_f32 v165, v186, v188
	v_cvt_pk_bf16_f32 v167, v212, v192
	v_fma_f32 v186, -v217, v180, v202
	v_exp_f32_e32 v192, v152
	v_fma_f32 v152, -v218, v237, v154
	v_cvt_pk_bf16_f32 v162, v211, v191
	v_pk_add_f32 v[122:123], v[122:123], v[194:195]
	v_exp_f32_e32 v191, v186
	v_fma_f32 v186, -v217, v236, v203
	v_exp_f32_e32 v194, v152
	v_fma_f32 v152, -v218, v238, v155
	v_cvt_pk_bf16_f32 v163, v213, v193
	v_exp_f32_e32 v193, v186
	v_fma_f32 v186, -v217, v237, v204
	v_exp_f32_e32 v196, v152
	v_fma_f32 v152, -v218, v239, v156
	v_exp_f32_e32 v195, v186
	v_fma_f32 v186, -v217, v238, v205
	v_exp_f32_e32 v198, v152
	v_fma_f32 v152, -v218, v240, v157
	v_exp_f32_e32 v197, v186
	v_fma_f32 v186, -v217, v239, v206
	v_exp_f32_e32 v200, v152
	v_fma_f32 v152, -v218, v241, v158
	v_exp_f32_e32 v199, v186
	v_fma_f32 v186, -v217, v240, v207
	v_exp_f32_e32 v202, v152
	v_pk_add_f32 v[152:153], v[190:191], 0 op_sel_hi:[1,0]
	v_exp_f32_e32 v201, v186
	v_fma_f32 v186, -v217, v241, v208
	v_pk_add_f32 v[152:153], v[192:193], v[152:153]
	v_exp_f32_e32 v203, v186
	v_fma_f32 v186, -v217, v151, v209
	v_fma_f32 v151, -v218, v151, v159
	v_pk_add_f32 v[152:153], v[194:195], v[152:153]
	v_exp_f32_e32 v205, v186
	v_exp_f32_e32 v204, v151
	v_pk_add_f32 v[152:153], v[196:197], v[152:153]
	v_cvt_pk_bf16_f32 v161, v187, v189
	v_pk_add_f32 v[152:153], v[198:199], v[152:153]
	v_cvt_pk_bf16_f32 v186, v191, v193
	v_pk_add_f32 v[152:153], v[200:201], v[152:153]
	v_cvt_pk_bf16_f32 v187, v195, v197
	v_pk_add_f32 v[152:153], v[202:203], v[152:153]
	v_cvt_pk_bf16_f32 v188, v199, v201
	v_pk_add_f32 v[152:153], v[204:205], v[152:153]
	v_cvt_pk_bf16_f32 v189, v203, v205
	v_pk_add_f32 v[120:121], v[120:121], v[152:153]
	v_cvt_pk_bf16_f32 v152, v190, v192
	v_cvt_pk_bf16_f32 v153, v194, v196
	v_cvt_pk_bf16_f32 v154, v198, v200
	v_cvt_pk_bf16_f32 v155, v202, v204
	s_waitcnt lgkmcnt(3)
	v_mfma_f32_16x16x32_bf16 v[34:37], v[168:171], v[160:163], v[34:37]
	s_waitcnt lgkmcnt(2)
	v_mfma_f32_16x16x32_bf16 v[38:41], v[172:175], v[160:163], v[38:41]
	s_waitcnt lgkmcnt(1)
	v_mfma_f32_16x16x32_bf16 v[42:45], v[176:179], v[160:163], v[42:45]
	s_waitcnt lgkmcnt(0)
	v_mfma_f32_16x16x32_bf16 v[46:49], v[182:185], v[160:163], v[46:49]
	v_mfma_f32_16x16x32_bf16 v[50:53], v[168:171], v[164:167], v[50:53]
	v_mfma_f32_16x16x32_bf16 v[54:57], v[172:175], v[164:167], v[54:57]
	v_mfma_f32_16x16x32_bf16 v[58:61], v[176:179], v[164:167], v[58:61]
	v_mfma_f32_16x16x32_bf16 v[62:65], v[182:185], v[164:167], v[62:65]
	v_mfma_f32_16x16x32_bf16 v[66:69], v[168:171], v[186:189], v[66:69]
	v_mfma_f32_16x16x32_bf16 v[70:73], v[172:175], v[186:189], v[70:73]
	v_mfma_f32_16x16x32_bf16 v[74:77], v[176:179], v[186:189], v[74:77]
	v_mfma_f32_16x16x32_bf16 v[78:81], v[182:185], v[186:189], v[78:81]
	v_mfma_f32_16x16x32_bf16 v[82:85], v[168:171], v[152:155], v[82:85]
	v_mfma_f32_16x16x32_bf16 v[86:89], v[172:175], v[152:155], v[86:89]
	v_mfma_f32_16x16x32_bf16 v[90:93], v[176:179], v[152:155], v[90:93]
	v_mfma_f32_16x16x32_bf16 v[94:97], v[182:185], v[152:155], v[94:97]
	s_mov_b32 s20, 1
	s_and_b64 vcc, exec, s[18:19]
	s_mov_b64 s[18:19], 0
	s_cbranch_vccnz .LBB0_2477

.LBB0_2494:
	s_lshl_b32 s57, s52, 5
	s_or_b32 s53, s57, s16
	s_cmp_gt_i32 s53, s46
	s_cselect_b64 s[74:75], -1, 0
	s_or_b32 s59, s53, 31
	s_cmp_lt_i32 s59, s24
	s_cselect_b64 s[76:77], -1, 0
	s_or_b64 s[74:75], s[74:75], s[76:77]
	s_and_b64 vcc, exec, s[74:75]
	s_cbranch_vccnz .LBB0_2493
	v_add_u32_e32 v182, s53, v144
	v_sub_u32_e32 v183, v227, v182
	v_cvt_f32_i32_e32 v184, v183
	v_xad_u32 v185, v182, -1, v227
	v_cvt_f32_i32_e32 v186, v185
	v_cmp_gt_u32_e32 vcc, s50, v183
	v_or_b32_e32 v183, 2, v182
	v_sub_u32_e32 v183, v227, v183
	v_cndmask_b32_e32 v210, v1, v184, vcc
	v_cmp_gt_u32_e32 vcc, s50, v185
	v_cvt_f32_i32_e32 v184, v183
	v_or_b32_e32 v185, 3, v182
	v_sub_u32_e32 v185, v227, v185
	v_cndmask_b32_e32 v211, v1, v186, vcc
	v_cvt_f32_i32_e32 v186, v185
	v_cmp_gt_u32_e32 vcc, s50, v183
	v_or_b32_e32 v183, 4, v182
	v_sub_u32_e32 v183, v227, v183
	v_or_b32_e32 v150, s57, v226
	v_cndmask_b32_e32 v212, v1, v184, vcc
	v_cvt_f32_i32_e32 v184, v183
	v_mad_u32_u24 v162, v150, s49, v131
	v_lshl_add_u32 v178, s52, 6, v148
	v_cmp_gt_u32_e32 vcc, s50, v185
	v_or_b32_e32 v185, 5, v182
	ds_read_b128 v[150:153], v162
	ds_read_b128 v[154:157], v162 offset:64
	ds_read_b128 v[158:161], v162 offset:2304
	ds_read_b128 v[162:165], v162 offset:2368
	ds_read_b128 v[166:169], v178 offset:9216
	ds_read_b128 v[170:173], v178 offset:11520
	ds_read_b128 v[174:177], v178 offset:13824
	ds_read_b128 v[178:181], v178 offset:16128
	v_cndmask_b32_e32 v213, v1, v186, vcc
	v_sub_u32_e32 v185, v227, v185
	v_cmp_gt_u32_e32 vcc, s50, v183
	v_or_b32_e32 v183, 6, v182
	v_cvt_f32_i32_e32 v186, v185
	v_sub_u32_e32 v183, v227, v183
	v_or_b32_e32 v182, 7, v182
	v_cndmask_b32_e32 v230, v1, v184, vcc
	v_cvt_f32_i32_e32 v184, v183
	v_sub_u32_e32 v182, v227, v182
	v_cmp_gt_u32_e32 vcc, s50, v185
	v_cvt_f32_i32_e32 v185, v182
	s_nop 0
	v_cndmask_b32_e32 v231, v1, v186, vcc
	v_cmp_gt_u32_e32 vcc, s50, v183
	s_nop 1
	v_cndmask_b32_e32 v232, v1, v184, vcc
	v_cmp_gt_u32_e32 vcc, s50, v182
	s_nop 1
	v_cndmask_b32_e32 v233, v1, v185, vcc
	s_waitcnt lgkmcnt(7)
	v_mfma_f32_16x16x32_bf16 v[182:185], v[150:153], v[2:5], 0
	v_mfma_f32_16x16x32_bf16 v[190:193], v[150:153], v[10:13], 0
	v_mfma_f32_16x16x32_bf16 v[198:201], v[150:153], v[18:21], 0
	v_mfma_f32_16x16x32_bf16 v[150:153], v[150:153], v[26:29], 0
	s_waitcnt lgkmcnt(6)
	v_mfma_f32_16x16x32_bf16 v[182:185], v[154:157], v[6:9], v[182:185]
	s_waitcnt lgkmcnt(5)
	v_mfma_f32_16x16x32_bf16 v[186:189], v[158:161], v[2:5], 0
	v_mfma_f32_16x16x32_bf16 v[190:193], v[154:157], v[14:17], v[190:193]
	v_mfma_f32_16x16x32_bf16 v[194:197], v[158:161], v[10:13], 0
	v_mfma_f32_16x16x32_bf16 v[198:201], v[154:157], v[22:25], v[198:201]
	v_mfma_f32_16x16x32_bf16 v[202:205], v[158:161], v[18:21], 0
	v_mfma_f32_16x16x32_bf16 v[150:153], v[154:157], v[30:33], v[150:153]
	v_mfma_f32_16x16x32_bf16 v[154:157], v[158:161], v[26:29], 0
	s_waitcnt lgkmcnt(4)
	v_mfma_f32_16x16x32_bf16 v[186:189], v[162:165], v[6:9], v[186:189]
	v_mfma_f32_16x16x32_bf16 v[194:197], v[162:165], v[14:17], v[194:197]
	v_mfma_f32_16x16x32_bf16 v[202:205], v[162:165], v[22:25], v[202:205]
	v_mfma_f32_16x16x32_bf16 v[154:157], v[162:165], v[30:33], v[154:157]
	v_fma_f32 v158, -v215, v210, v182
	v_fma_f32 v162, -v216, v210, v190
	v_exp_f32_e32 v163, v158
	v_fma_f32 v158, -v215, v211, v183
	v_exp_f32_e32 v162, v162
	v_fma_f32 v164, -v216, v211, v191
	v_exp_f32_e32 v165, v158
	v_fma_f32 v158, -v215, v212, v184
	v_exp_f32_e32 v164, v164
	v_fma_f32 v182, -v216, v212, v192
	v_exp_f32_e32 v183, v158
	v_fma_f32 v158, -v215, v213, v185
	v_exp_f32_e32 v182, v182
	v_fma_f32 v184, -v216, v213, v193
	v_exp_f32_e32 v185, v158
	v_fma_f32 v158, -v215, v230, v186
	v_exp_f32_e32 v184, v184
	v_fma_f32 v186, -v216, v230, v194
	v_exp_f32_e32 v207, v158
	v_fma_f32 v158, -v215, v231, v187
	v_exp_f32_e32 v206, v186
	v_fma_f32 v186, -v216, v231, v195
	v_pk_add_f32 v[190:191], v[162:163], 0 op_sel_hi:[1,0]
	v_exp_f32_e32 v187, v158
	v_fma_f32 v158, -v215, v232, v188
	v_exp_f32_e32 v186, v186
	v_fma_f32 v188, -v216, v232, v196
	v_pk_add_f32 v[190:191], v[164:165], v[190:191]
	v_exp_f32_e32 v209, v158
	v_fma_f32 v158, -v215, v233, v189
	v_exp_f32_e32 v208, v188
	v_fma_f32 v188, -v216, v233, v197
	v_pk_add_f32 v[190:191], v[182:183], v[190:191]
	v_exp_f32_e32 v189, v158
	v_exp_f32_e32 v188, v188
	v_pk_add_f32 v[190:191], v[184:185], v[190:191]
	v_fma_f32 v150, -v218, v210, v150
	v_pk_add_f32 v[190:191], v[206:207], v[190:191]
	v_cvt_pk_bf16_f32 v162, v162, v164
	v_pk_add_f32 v[190:191], v[186:187], v[190:191]
	v_cvt_pk_bf16_f32 v164, v206, v186
	v_pk_add_f32 v[190:191], v[208:209], v[190:191]
	v_exp_f32_e32 v186, v150
	v_fma_f32 v150, -v218, v211, v151
	v_cvt_pk_bf16_f32 v158, v163, v165
	v_pk_add_f32 v[190:191], v[188:189], v[190:191]
	v_cvt_pk_bf16_f32 v165, v208, v188
	v_exp_f32_e32 v188, v150
	v_fma_f32 v150, -v218, v212, v152
	v_pk_add_f32 v[122:123], v[122:123], v[190:191]
	v_cvt_pk_bf16_f32 v163, v182, v184
	v_fma_f32 v182, -v217, v210, v198
	v_exp_f32_e32 v190, v150
	v_fma_f32 v150, -v218, v213, v153
	v_cvt_pk_bf16_f32 v160, v207, v187
	v_exp_f32_e32 v187, v182
	v_fma_f32 v182, -v217, v211, v199
	v_exp_f32_e32 v192, v150
	v_fma_f32 v150, -v218, v230, v154
	v_cvt_pk_bf16_f32 v161, v209, v189
	v_exp_f32_e32 v189, v182
	v_fma_f32 v182, -v217, v212, v200
	v_exp_f32_e32 v194, v150
	v_fma_f32 v150, -v218, v231, v155
	v_exp_f32_e32 v191, v182
	v_fma_f32 v182, -v217, v213, v201
	v_exp_f32_e32 v196, v150
	v_fma_f32 v150, -v218, v232, v156
	v_exp_f32_e32 v193, v182
	v_fma_f32 v182, -v217, v230, v202
	v_exp_f32_e32 v198, v150
	v_fma_f32 v150, -v218, v233, v157
	v_exp_f32_e32 v195, v182
	v_fma_f32 v182, -v217, v231, v203
	v_exp_f32_e32 v200, v150
	v_pk_add_f32 v[150:151], v[186:187], 0 op_sel_hi:[1,0]
	v_exp_f32_e32 v197, v182
	v_fma_f32 v182, -v217, v232, v204
	v_pk_add_f32 v[150:151], v[188:189], v[150:151]
	v_exp_f32_e32 v199, v182
	v_fma_f32 v182, -v217, v233, v205
	v_pk_add_f32 v[150:151], v[190:191], v[150:151]
	v_exp_f32_e32 v201, v182
	v_pk_add_f32 v[150:151], v[192:193], v[150:151]
	v_cvt_pk_bf16_f32 v159, v183, v185
	v_pk_add_f32 v[150:151], v[194:195], v[150:151]
	v_cvt_pk_bf16_f32 v182, v187, v189
	v_pk_add_f32 v[150:151], v[196:197], v[150:151]
	v_cvt_pk_bf16_f32 v183, v191, v193
	v_pk_add_f32 v[150:151], v[198:199], v[150:151]
	v_cvt_pk_bf16_f32 v184, v195, v197
	v_pk_add_f32 v[150:151], v[200:201], v[150:151]
	v_cvt_pk_bf16_f32 v185, v199, v201
	v_pk_add_f32 v[120:121], v[120:121], v[150:151]
	v_cvt_pk_bf16_f32 v150, v186, v188
	v_cvt_pk_bf16_f32 v151, v190, v192
	v_cvt_pk_bf16_f32 v152, v194, v196
	v_cvt_pk_bf16_f32 v153, v198, v200
	s_waitcnt lgkmcnt(3)
	v_mfma_f32_16x16x32_bf16 v[94:97], v[166:169], v[158:161], v[94:97]
	s_waitcnt lgkmcnt(2)
	v_mfma_f32_16x16x32_bf16 v[90:93], v[170:173], v[158:161], v[90:93]
	s_waitcnt lgkmcnt(1)
	v_mfma_f32_16x16x32_bf16 v[86:89], v[174:177], v[158:161], v[86:89]
	s_waitcnt lgkmcnt(0)
	v_mfma_f32_16x16x32_bf16 v[82:85], v[178:181], v[158:161], v[82:85]
	v_mfma_f32_16x16x32_bf16 v[78:81], v[166:169], v[162:165], v[78:81]
	v_mfma_f32_16x16x32_bf16 v[74:77], v[170:173], v[162:165], v[74:77]
	v_mfma_f32_16x16x32_bf16 v[70:73], v[174:177], v[162:165], v[70:73]
	v_mfma_f32_16x16x32_bf16 v[66:69], v[178:181], v[162:165], v[66:69]
	v_mfma_f32_16x16x32_bf16 v[62:65], v[166:169], v[182:185], v[62:65]
	v_mfma_f32_16x16x32_bf16 v[58:61], v[170:173], v[182:185], v[58:61]
	v_mfma_f32_16x16x32_bf16 v[54:57], v[174:177], v[182:185], v[54:57]
	v_mfma_f32_16x16x32_bf16 v[50:53], v[178:181], v[182:185], v[50:53]
	v_mfma_f32_16x16x32_bf16 v[46:49], v[166:169], v[150:153], v[46:49]
	v_mfma_f32_16x16x32_bf16 v[42:45], v[170:173], v[150:153], v[42:45]
	v_mfma_f32_16x16x32_bf16 v[38:41], v[174:177], v[150:153], v[38:41]
	v_mfma_f32_16x16x32_bf16 v[34:37], v[178:181], v[150:153], v[34:37]
	s_branch .LBB0_2493

.LBB0_2515:
	s_or_b32 s52, s53, s20
	s_lshl_b32 s57, s52, 4
	s_cmp_ge_i32 s57, s24
	s_cbranch_scc1 .LBB0_2514
	v_or_b32_e32 v57, s53, v226
	v_mad_u32_u24 v57, v57, s49, v46
	ds_read_b128 v[58:61], v57
	ds_read_b128 v[62:65], v57 offset:64
	ds_read_b128 v[66:69], v57 offset:2304
	ds_read_b128 v[70:73], v57 offset:2368
	v_subrev_u32_e32 v57, s52, v48
	v_lshl_add_u32 v57, v57, 4, v49
	v_cvt_f32_u32_e32 v74, v57
	v_xad_u32 v75, s52, -1, v48
	v_lshl_add_u32 v75, v75, 4, v49
	v_cvt_f32_u32_e32 v76, v75
	v_cmp_gt_u32_e32 vcc, 2.0, v57
	s_nop 1
	v_cndmask_b32_e32 v57, v56, v74, vcc
	v_subrev_u32_e32 v74, s52, v50
	v_cmp_gt_u32_e32 vcc, 2.0, v75
	v_lshl_add_u32 v74, v74, 4, v49
	v_cvt_f32_u32_e32 v75, v74
	v_cndmask_b32_e32 v98, v56, v76, vcc
	v_subrev_u32_e32 v76, s52, v51
	v_lshl_add_u32 v76, v76, 4, v49
	v_cvt_f32_u32_e32 v77, v76
	v_cmp_gt_u32_e32 vcc, 2.0, v74
	v_subrev_u32_e32 v74, s52, v52
	v_lshl_add_u32 v74, v74, 4, v49
	v_cndmask_b32_e32 v99, v56, v75, vcc
	v_cmp_gt_u32_e32 vcc, 2.0, v76
	v_cvt_f32_u32_e32 v75, v74
	v_subrev_u32_e32 v76, s52, v53
	v_lshl_add_u32 v76, v76, 4, v49
	v_cndmask_b32_e32 v100, v56, v77, vcc
	v_cvt_f32_u32_e32 v77, v76
	v_cmp_gt_u32_e32 vcc, 2.0, v74
	v_subrev_u32_e32 v74, s52, v54
	v_lshl_add_u32 v74, v74, 4, v49
	v_cndmask_b32_e32 v101, v56, v75, vcc
	v_cmp_gt_u32_e32 vcc, 2.0, v76
	v_subrev_u32_e32 v76, s52, v55
	v_cvt_f32_u32_e32 v75, v74
	v_lshl_add_u32 v76, v76, 4, v49
	v_cndmask_b32_e32 v102, v56, v77, vcc
	v_cvt_f32_u32_e32 v77, v76
	v_cmp_gt_u32_e32 vcc, 2.0, v74
	s_nop 1
	v_cndmask_b32_e32 v103, v56, v75, vcc
	v_cmp_gt_u32_e32 vcc, 2.0, v76
	s_nop 1
	v_cndmask_b32_e32 v104, v56, v77, vcc
	s_waitcnt vmcnt(7) lgkmcnt(3)
	v_mfma_f32_16x16x32_bf16 v[74:77], v[58:61], v[2:5], 0
	s_waitcnt vmcnt(5)
	v_mfma_f32_16x16x32_bf16 v[82:85], v[58:61], v[10:13], 0
	s_waitcnt vmcnt(3)
	v_mfma_f32_16x16x32_bf16 v[90:93], v[58:61], v[18:21], 0
	s_waitcnt vmcnt(1)
	v_mfma_f32_16x16x32_bf16 v[58:61], v[58:61], v[26:29], 0
	s_waitcnt lgkmcnt(2)
	v_mfma_f32_16x16x32_bf16 v[74:77], v[62:65], v[6:9], v[74:77]
	s_waitcnt lgkmcnt(1)
	v_mfma_f32_16x16x32_bf16 v[78:81], v[66:69], v[2:5], 0
	v_mfma_f32_16x16x32_bf16 v[82:85], v[62:65], v[14:17], v[82:85]
	v_mfma_f32_16x16x32_bf16 v[86:89], v[66:69], v[10:13], 0
	v_mfma_f32_16x16x32_bf16 v[90:93], v[62:65], v[22:25], v[90:93]
	v_mfma_f32_16x16x32_bf16 v[94:97], v[66:69], v[18:21], 0
	s_waitcnt vmcnt(0)
	v_mfma_f32_16x16x32_bf16 v[58:61], v[62:65], v[30:33], v[58:61]
	v_mfma_f32_16x16x32_bf16 v[62:65], v[66:69], v[26:29], 0
	s_waitcnt lgkmcnt(0)
	v_mfma_f32_16x16x32_bf16 v[78:81], v[70:73], v[6:9], v[78:81]
	v_mfma_f32_16x16x32_bf16 v[86:89], v[70:73], v[14:17], v[86:89]
	v_mfma_f32_16x16x32_bf16 v[94:97], v[70:73], v[22:25], v[94:97]
	v_mfma_f32_16x16x32_bf16 v[62:65], v[70:73], v[30:33], v[62:65]
	v_fma_f32 v66, -v215, v57, v74
	v_exp_f32_e32 v67, v66
	v_fma_f32 v66, -v215, v98, v75
	v_exp_f32_e32 v69, v66
	v_fma_f32 v66, -v215, v99, v76
	v_exp_f32_e32 v71, v66
	v_fma_f32 v66, -v215, v100, v77
	v_exp_f32_e32 v73, v66
	v_fma_f32 v66, -v215, v101, v78
	v_exp_f32_e32 v75, v66
	v_fma_f32 v66, -v215, v102, v79
	v_exp_f32_e32 v77, v66
	v_fma_f32 v66, -v215, v103, v80
	v_exp_f32_e32 v79, v66
	v_fma_f32 v66, -v215, v104, v81
	v_exp_f32_e32 v81, v66
	v_fma_f32 v66, -v216, v57, v82
	v_exp_f32_e32 v66, v66
	v_fma_f32 v68, -v216, v98, v83
	v_exp_f32_e32 v68, v68
	v_fma_f32 v70, -v216, v99, v84
	v_exp_f32_e32 v70, v70
	v_fma_f32 v72, -v216, v100, v85
	v_exp_f32_e32 v72, v72
	v_fma_f32 v74, -v216, v101, v86
	v_exp_f32_e32 v74, v74
	v_fma_f32 v76, -v216, v102, v87
	v_pk_add_f32 v[66:67], v[66:67], 0 op_sel_hi:[1,0]
	v_exp_f32_e32 v76, v76
	v_fma_f32 v78, -v216, v103, v88
	v_pk_add_f32 v[66:67], v[68:69], v[66:67]
	v_exp_f32_e32 v78, v78
	v_fma_f32 v80, -v216, v104, v89
	v_pk_add_f32 v[66:67], v[70:71], v[66:67]
	v_exp_f32_e32 v80, v80
	v_pk_add_f32 v[66:67], v[72:73], v[66:67]
	s_nop 0
	v_pk_add_f32 v[66:67], v[74:75], v[66:67]
	s_nop 0
	v_pk_add_f32 v[66:67], v[76:77], v[66:67]
	s_nop 0
	v_pk_add_f32 v[66:67], v[78:79], v[66:67]
	s_nop 0
	v_pk_add_f32 v[66:67], v[80:81], v[66:67]
	s_nop 0
	v_pk_add_f32 v[44:45], v[44:45], v[66:67]
	v_fma_f32 v66, -v217, v57, v90
	v_exp_f32_e32 v67, v66
	v_fma_f32 v66, -v217, v98, v91
	v_exp_f32_e32 v69, v66
	v_fma_f32 v66, -v217, v99, v92
	v_exp_f32_e32 v71, v66
	v_fma_f32 v66, -v217, v100, v93
	v_exp_f32_e32 v73, v66
	v_fma_f32 v66, -v217, v101, v94
	v_exp_f32_e32 v75, v66
	v_fma_f32 v66, -v217, v102, v95
	v_exp_f32_e32 v77, v66
	v_fma_f32 v66, -v217, v103, v96
	v_exp_f32_e32 v79, v66
	v_fma_f32 v66, -v217, v104, v97
	v_fma_f32 v57, -v218, v57, v58
	v_exp_f32_e32 v81, v66
	v_exp_f32_e32 v66, v57
	v_fma_f32 v57, -v218, v98, v59
	v_exp_f32_e32 v68, v57
	v_fma_f32 v57, -v218, v99, v60
	v_exp_f32_e32 v70, v57
	v_fma_f32 v57, -v218, v100, v61
	v_exp_f32_e32 v72, v57
	v_fma_f32 v57, -v218, v101, v62
	v_exp_f32_e32 v74, v57
	v_fma_f32 v57, -v218, v102, v63
	v_pk_add_f32 v[58:59], v[66:67], 0 op_sel_hi:[1,0]
	v_exp_f32_e32 v76, v57
	v_fma_f32 v57, -v218, v103, v64
	v_pk_add_f32 v[58:59], v[68:69], v[58:59]
	v_exp_f32_e32 v78, v57
	v_fma_f32 v57, -v218, v104, v65
	v_pk_add_f32 v[58:59], v[70:71], v[58:59]
	v_exp_f32_e32 v80, v57
	v_pk_add_f32 v[58:59], v[72:73], v[58:59]
	s_nop 0
	v_pk_add_f32 v[58:59], v[74:75], v[58:59]
	s_nop 0
	v_pk_add_f32 v[58:59], v[76:77], v[58:59]
	s_nop 0
	v_pk_add_f32 v[58:59], v[78:79], v[58:59]
	s_nop 0
	v_pk_add_f32 v[58:59], v[80:81], v[58:59]
	s_nop 0
	v_pk_add_f32 v[42:43], v[42:43], v[58:59]
	s_branch .LBB0_2514

.LBB0_2529:
	s_lshl_b32 s57, s53, 5
	s_or_b32 s52, s57, s16
	s_lshl_b32 s59, s52, 4
	s_cmp_ge_i32 s59, s24
	s_cbranch_scc1 .LBB0_2528
	v_subrev_u32_e32 v175, s52, v163
	v_lshl_add_u32 v175, v175, 4, v164
	v_cvt_f32_u32_e32 v192, v175
	v_xad_u32 v193, s52, -1, v163
	v_lshl_add_u32 v193, v193, 4, v164
	v_cvt_f32_u32_e32 v194, v193
	v_cmp_gt_u32_e32 vcc, 2.0, v175
	v_or_b32_e32 v108, s57, v226
	v_mad_u32_u24 v108, v108, s49, v98
	v_cndmask_b32_e32 v175, v173, v192, vcc
	v_subrev_u32_e32 v192, s52, v165
	v_cmp_gt_u32_e32 vcc, 2.0, v193
	v_lshl_add_u32 v192, v192, 4, v164
	v_cvt_f32_u32_e32 v193, v192
	v_cndmask_b32_e32 v212, v173, v194, vcc
	v_subrev_u32_e32 v194, s52, v166
	v_lshl_add_u32 v194, v194, 4, v164
	v_cvt_f32_u32_e32 v195, v194
	v_cmp_gt_u32_e32 vcc, 2.0, v192
	v_subrev_u32_e32 v192, s52, v167
	v_lshl_add_u32 v192, v192, 4, v164
	v_cndmask_b32_e32 v213, v173, v193, vcc
	v_cmp_gt_u32_e32 vcc, 2.0, v194
	v_cvt_f32_u32_e32 v193, v192
	v_subrev_u32_e32 v194, s52, v168
	v_lshl_add_u32 v194, v194, 4, v164
	v_lshl_add_u32 v120, s53, 6, v174
	v_cndmask_b32_e32 v231, v173, v195, vcc
	v_cvt_f32_u32_e32 v195, v194
	ds_read_b128 v[176:179], v108
	ds_read_b128 v[180:183], v108 offset:64
	ds_read_b128 v[184:187], v108 offset:2304
	ds_read_b128 v[188:191], v108 offset:2368
	ds_read_b128 v[108:111], v120 offset:9216
	ds_read_b128 v[112:115], v120 offset:11520
	ds_read_b128 v[116:119], v120 offset:13824
	ds_read_b128 v[120:123], v120 offset:16128
	v_cmp_gt_u32_e32 vcc, 2.0, v192
	v_subrev_u32_e32 v192, s52, v169
	v_lshl_add_u32 v192, v192, 4, v164
	v_cndmask_b32_e32 v236, v173, v193, vcc
	v_cmp_gt_u32_e32 vcc, 2.0, v194
	v_subrev_u32_e32 v194, s52, v170
	v_cvt_f32_u32_e32 v193, v192
	v_lshl_add_u32 v194, v194, 4, v164
	v_cndmask_b32_e32 v237, v173, v195, vcc
	v_cvt_f32_u32_e32 v195, v194
	v_cmp_gt_u32_e32 vcc, 2.0, v192
	s_nop 1
	v_cndmask_b32_e32 v238, v173, v193, vcc
	v_cmp_gt_u32_e32 vcc, 2.0, v194
	s_nop 1
	v_cndmask_b32_e32 v239, v173, v195, vcc
	s_waitcnt lgkmcnt(7)
	v_mfma_f32_16x16x32_bf16 v[192:195], v[176:179], v[2:5], 0
	v_mfma_f32_16x16x32_bf16 v[200:203], v[176:179], v[10:13], 0
	v_mfma_f32_16x16x32_bf16 v[208:211], v[176:179], v[18:21], 0
	v_mfma_f32_16x16x32_bf16 v[176:179], v[176:179], v[26:29], 0
	s_waitcnt lgkmcnt(6)
	v_mfma_f32_16x16x32_bf16 v[192:195], v[180:183], v[6:9], v[192:195]
	s_waitcnt lgkmcnt(5)
	v_mfma_f32_16x16x32_bf16 v[196:199], v[184:187], v[2:5], 0
	v_mfma_f32_16x16x32_bf16 v[200:203], v[180:183], v[14:17], v[200:203]
	v_mfma_f32_16x16x32_bf16 v[204:207], v[184:187], v[10:13], 0
	v_mfma_f32_16x16x32_bf16 v[208:211], v[180:183], v[22:25], v[208:211]
	v_mfma_f32_16x16x32_bf16 v[232:235], v[184:187], v[18:21], 0
	v_mfma_f32_16x16x32_bf16 v[176:179], v[180:183], v[30:33], v[176:179]
	v_mfma_f32_16x16x32_bf16 v[180:183], v[184:187], v[26:29], 0
	s_waitcnt lgkmcnt(4)
	v_mfma_f32_16x16x32_bf16 v[196:199], v[188:191], v[6:9], v[196:199]
	v_mfma_f32_16x16x32_bf16 v[204:207], v[188:191], v[14:17], v[204:207]
	v_mfma_f32_16x16x32_bf16 v[232:235], v[188:191], v[22:25], v[232:235]
	v_mfma_f32_16x16x32_bf16 v[180:183], v[188:191], v[30:33], v[180:183]
	v_fma_f32 v184, -v215, v175, v192
	v_fma_f32 v185, -v215, v212, v193
	v_fma_f32 v186, -v215, v213, v194
	v_fma_f32 v187, -v215, v231, v195
	v_exp_f32_e32 v184, v184
	v_exp_f32_e32 v185, v185
	v_exp_f32_e32 v186, v186
	v_exp_f32_e32 v187, v187
	v_fma_f32 v188, -v215, v236, v196
	v_fma_f32 v189, -v215, v237, v197
	v_fma_f32 v190, -v215, v238, v198
	v_fma_f32 v191, -v215, v239, v199
	v_exp_f32_e32 v188, v188
	v_exp_f32_e32 v189, v189
	v_exp_f32_e32 v190, v190
	v_exp_f32_e32 v191, v191
	v_pk_mul_f32 v[184:185], v[150:151], v[184:185]
	v_pk_mul_f32 v[186:187], v[150:151], v[186:187]
	v_add_f32_e32 v193, v184, v185
	v_add_f32_e32 v192, v186, v187
	v_pk_mul_f32 v[188:189], v[150:151], v[188:189]
	v_pk_mul_f32 v[190:191], v[150:151], v[190:191]
	v_add_f32_e32 v192, v193, v192
	v_add_f32_e32 v196, 0, v192
	v_add_f32_e32 v192, v190, v191
	v_add_f32_e32 v193, v188, v189
	v_add_f32_e32 v197, 0, v187
	v_add_f32_e32 v192, v193, v192
	v_add_f32_e32 v199, 0, v191
	v_cvt_pk_bf16_f32 v184, v184, v185
	v_cvt_pk_bf16_f32 v185, v186, v187
	v_cvt_pk_bf16_f32 v186, v188, v189
	v_cvt_pk_bf16_f32 v187, v190, v191
	v_fma_f32 v188, -v216, v175, v200
	v_fma_f32 v189, -v216, v212, v201
	v_fma_f32 v190, -v216, v213, v202
	v_fma_f32 v191, -v216, v231, v203
	v_add_f32_e32 v198, 0, v192
	v_exp_f32_e32 v188, v188
	v_exp_f32_e32 v189, v189
	v_exp_f32_e32 v190, v190
	v_exp_f32_e32 v191, v191
	v_fma_f32 v192, -v216, v236, v204
	v_fma_f32 v193, -v216, v237, v205
	v_exp_f32_e32 v192, v192
	v_exp_f32_e32 v193, v193
	v_fma_f32 v194, -v216, v238, v206
	v_fma_f32 v195, -v216, v239, v207
	v_pk_mul_f32 v[188:189], v[152:153], v[188:189]
	v_pk_mul_f32 v[190:191], v[152:153], v[190:191]
	v_exp_f32_e32 v194, v194
	v_exp_f32_e32 v195, v195
	v_pk_mul_f32 v[192:193], v[152:153], v[192:193]
	v_add_f32_e32 v200, v190, v191
	v_add_f32_e32 v201, v188, v189
	v_add_f32_e32 v200, v201, v200
	v_add_f32_e32 v201, v197, v191
	v_add_f32_e32 v197, v192, v193
	v_cvt_pk_bf16_f32 v188, v188, v189
	v_cvt_pk_bf16_f32 v189, v190, v191
	v_cvt_pk_bf16_f32 v190, v192, v193
	v_fma_f32 v192, -v217, v175, v208
	v_fma_f32 v175, -v218, v175, v176
	v_exp_f32_e32 v176, v175
	v_fma_f32 v175, -v218, v212, v177
	v_exp_f32_e32 v177, v175
	v_fma_f32 v175, -v218, v213, v178
	v_pk_mul_f32 v[194:195], v[152:153], v[194:195]
	v_exp_f32_e32 v178, v175
	v_fma_f32 v175, -v218, v231, v179
	v_add_f32_e32 v200, v196, v200
	v_add_f32_e32 v196, v194, v195
	v_add_f32_e32 v203, v199, v195
	v_cvt_pk_bf16_f32 v191, v194, v195
	v_fma_f32 v193, -v217, v212, v209
	v_fma_f32 v194, -v217, v213, v210
	v_fma_f32 v195, -v217, v231, v211
	v_exp_f32_e32 v179, v175
	v_fma_f32 v175, -v218, v236, v180
	v_add_f32_e32 v196, v197, v196
	v_exp_f32_e32 v192, v192
	v_exp_f32_e32 v193, v193
	v_exp_f32_e32 v194, v194
	v_exp_f32_e32 v195, v195
	v_exp_f32_e32 v180, v175
	v_fma_f32 v175, -v218, v237, v181
	v_add_f32_e32 v202, v198, v196
	v_fma_f32 v196, -v217, v236, v232
	v_fma_f32 v197, -v217, v237, v233
	v_fma_f32 v198, -v217, v238, v234
	v_fma_f32 v199, -v217, v239, v235
	v_exp_f32_e32 v181, v175
	v_fma_f32 v175, -v218, v238, v182
	v_exp_f32_e32 v196, v196
	v_exp_f32_e32 v197, v197
	v_exp_f32_e32 v198, v198
	v_exp_f32_e32 v199, v199
	v_exp_f32_e32 v182, v175
	v_fma_f32 v175, -v218, v239, v183
	v_exp_f32_e32 v183, v175
	v_pk_mul_f32 v[192:193], v[154:155], v[192:193]
	v_pk_mul_f32 v[194:195], v[154:155], v[194:195]
	v_add_f32_e32 v205, v192, v193
	v_add_f32_e32 v204, v194, v195
	v_pk_mul_f32 v[196:197], v[154:155], v[196:197]
	v_pk_mul_f32 v[198:199], v[154:155], v[198:199]
	v_add_f32_e32 v204, v205, v204
	v_add_f32_e32 v200, v200, v204
	v_add_f32_e32 v204, v198, v199
	v_add_f32_e32 v205, v196, v197
	v_pk_mul_f32 v[176:177], v[156:157], v[176:177]
	v_pk_mul_f32 v[178:179], v[156:157], v[178:179]
	v_pk_mul_f32 v[180:181], v[156:157], v[180:181]
	v_pk_mul_f32 v[182:183], v[156:157], v[182:183]
	v_add_f32_e32 v201, v201, v195
	v_add_f32_e32 v204, v205, v204
	v_cvt_pk_bf16_f32 v192, v192, v193
	v_cvt_pk_bf16_f32 v193, v194, v195
	v_cvt_pk_bf16_f32 v194, v196, v197
	v_cvt_pk_bf16_f32 v195, v198, v199
	v_add_f32_e32 v175, v178, v179
	v_add_f32_e32 v196, v176, v177
	v_add_f32_e32 v197, v182, v183
	v_add_f32_e32 v198, v180, v181
	v_add_f32_e32 v202, v202, v204
	v_add_f32_e32 v203, v203, v199
	v_add_f32_e32 v175, v196, v175
	v_add_f32_e32 v197, v198, v197
	v_add_f32_e32 v175, v200, v175
	v_add_f32_e32 v196, v201, v179
	v_add_f32_e32 v197, v202, v197
	v_add_f32_e32 v198, v203, v183
	v_cvt_pk_bf16_f32 v176, v176, v177
	v_cvt_pk_bf16_f32 v177, v178, v179
	v_cvt_pk_bf16_f32 v178, v180, v181
	v_cvt_pk_bf16_f32 v179, v182, v183
	s_waitcnt lgkmcnt(3)
	v_mfma_f32_16x16x32_bf16 v[94:97], v[108:111], v[184:187], v[94:97]
	s_waitcnt lgkmcnt(2)
	v_mfma_f32_16x16x32_bf16 v[90:93], v[112:115], v[184:187], v[90:93]
	s_waitcnt lgkmcnt(1)
	v_mfma_f32_16x16x32_bf16 v[86:89], v[116:119], v[184:187], v[86:89]
	s_waitcnt lgkmcnt(0)
	v_mfma_f32_16x16x32_bf16 v[82:85], v[120:123], v[184:187], v[82:85]
	v_mfma_f32_16x16x32_bf16 v[78:81], v[108:111], v[188:191], v[78:81]
	v_mfma_f32_16x16x32_bf16 v[74:77], v[112:115], v[188:191], v[74:77]
	v_mfma_f32_16x16x32_bf16 v[70:73], v[116:119], v[188:191], v[70:73]
	v_mfma_f32_16x16x32_bf16 v[66:69], v[120:123], v[188:191], v[66:69]
	v_mfma_f32_16x16x32_bf16 v[62:65], v[108:111], v[192:195], v[62:65]
	v_mfma_f32_16x16x32_bf16 v[58:61], v[112:115], v[192:195], v[58:61]
	v_mfma_f32_16x16x32_bf16 v[54:57], v[116:119], v[192:195], v[54:57]
	v_mfma_f32_16x16x32_bf16 v[50:53], v[120:123], v[192:195], v[50:53]
	v_mfma_f32_16x16x32_bf16 v[46:49], v[108:111], v[176:179], v[46:49]
	v_mfma_f32_16x16x32_bf16 v[42:45], v[112:115], v[176:179], v[42:45]
	v_mfma_f32_16x16x32_bf16 v[38:41], v[116:119], v[176:179], v[38:41]
	v_mfma_f32_16x16x32_bf16 v[34:37], v[120:123], v[176:179], v[34:37]
	v_add_u32_e32 v108, s52, v171
	ds_add_f32 v108, v175
	ds_add_f32 v108, v196 offset:4
	ds_add_f32 v108, v197 offset:4
	ds_add_f32 v108, v198 offset:8
	s_branch .LBB0_2528

.LBB0_2689:
	s_lshl_b32 s21, s20, 5
	v_or_b32_e32 v151, s21, v226
	v_mad_u32_u24 v151, v151, s52, v148
	ds_read_b128 v[152:155], v151
	ds_read_b128 v[156:159], v151 offset:64
	ds_read_b128 v[160:163], v151 offset:2304
	ds_read_b128 v[164:167], v151 offset:2368
	v_lshl_add_u32 v151, s20, 6, v149
	ds_read_b128 v[168:171], v151 offset:9216
	ds_read_b128 v[172:175], v151 offset:11520
	ds_read_b128 v[176:179], v151 offset:13824
	ds_read_b128 v[182:185], v151 offset:16128
	v_add_u32_e32 v151, s21, v150
	v_sub_u32_e32 v180, v227, v151
	v_cmp_gt_u32_e32 vcc, 2.0, v180
	v_cvt_f32_i32_e32 v180, v180
	v_xad_u32 v186, v151, -1, v227
	v_cvt_f32_i32_e32 v187, v186
	s_and_b64 vcc, s[16:17], vcc
	v_cndmask_b32_e32 v180, v233, v180, vcc
	v_cmp_gt_u32_e32 vcc, 2.0, v186
	v_or_b32_e32 v186, 2, v151
	s_and_b64 vcc, s[16:17], vcc
	v_sub_u32_e32 v186, v227, v186
	v_cndmask_b32_e32 v234, v233, v187, vcc
	v_cmp_gt_u32_e32 vcc, 2.0, v186
	v_cvt_f32_i32_e32 v186, v186
	v_or_b32_e32 v187, 3, v151
	v_sub_u32_e32 v187, v227, v187
	v_cvt_f32_i32_e32 v188, v187
	s_and_b64 vcc, s[16:17], vcc
	v_cndmask_b32_e32 v235, v233, v186, vcc
	v_cmp_gt_u32_e32 vcc, 2.0, v187
	v_or_b32_e32 v186, 4, v151
	s_and_b64 vcc, s[16:17], vcc
	v_sub_u32_e32 v186, v227, v186
	v_cndmask_b32_e32 v236, v233, v188, vcc
	v_cmp_gt_u32_e32 vcc, 2.0, v186
	v_cvt_f32_i32_e32 v186, v186
	v_or_b32_e32 v187, 5, v151
	v_sub_u32_e32 v187, v227, v187
	v_cvt_f32_i32_e32 v188, v187
	s_and_b64 vcc, s[16:17], vcc
	v_cndmask_b32_e32 v237, v233, v186, vcc
	v_cmp_gt_u32_e32 vcc, 2.0, v187
	v_or_b32_e32 v186, 6, v151
	s_and_b64 vcc, s[16:17], vcc
	v_sub_u32_e32 v186, v227, v186
	v_cndmask_b32_e32 v238, v233, v188, vcc
	v_cmp_gt_u32_e32 vcc, 2.0, v186
	v_cvt_f32_i32_e32 v186, v186
	v_or_b32_e32 v151, 7, v151
	v_sub_u32_e32 v151, v227, v151
	v_cvt_f32_i32_e32 v187, v151
	s_and_b64 vcc, s[16:17], vcc
	v_cndmask_b32_e32 v239, v233, v186, vcc
	v_cmp_gt_u32_e32 vcc, 2.0, v151
	s_and_b64 vcc, s[16:17], vcc
	s_nop 0
	v_cndmask_b32_e32 v151, v233, v187, vcc
	s_waitcnt lgkmcnt(7)
	v_mfma_f32_16x16x32_bf16 v[186:189], v[152:155], v[2:5], 0
	v_mfma_f32_16x16x32_bf16 v[194:197], v[152:155], v[10:13], 0
	v_mfma_f32_16x16x32_bf16 v[202:205], v[152:155], v[18:21], 0
	v_mfma_f32_16x16x32_bf16 v[152:155], v[152:155], v[26:29], 0
	s_waitcnt lgkmcnt(6)
	v_mfma_f32_16x16x32_bf16 v[186:189], v[156:159], v[6:9], v[186:189]
	s_waitcnt lgkmcnt(5)
	v_mfma_f32_16x16x32_bf16 v[190:193], v[160:163], v[2:5], 0
	v_mfma_f32_16x16x32_bf16 v[194:197], v[156:159], v[14:17], v[194:197]
	v_mfma_f32_16x16x32_bf16 v[198:201], v[160:163], v[10:13], 0
	v_mfma_f32_16x16x32_bf16 v[202:205], v[156:159], v[22:25], v[202:205]
	v_mfma_f32_16x16x32_bf16 v[206:209], v[160:163], v[18:21], 0
	v_mfma_f32_16x16x32_bf16 v[152:155], v[156:159], v[30:33], v[152:155]
	v_mfma_f32_16x16x32_bf16 v[156:159], v[160:163], v[26:29], 0
	s_waitcnt lgkmcnt(4)
	v_mfma_f32_16x16x32_bf16 v[190:193], v[164:167], v[6:9], v[190:193]
	v_mfma_f32_16x16x32_bf16 v[198:201], v[164:167], v[14:17], v[198:201]
	v_mfma_f32_16x16x32_bf16 v[206:209], v[164:167], v[22:25], v[206:209]
	v_mfma_f32_16x16x32_bf16 v[156:159], v[164:167], v[30:33], v[156:159]
	v_fma_f32 v160, -v215, v180, v186
	v_fma_f32 v164, -v216, v180, v194
	v_exp_f32_e32 v165, v160
	v_fma_f32 v160, -v215, v234, v187
	v_exp_f32_e32 v164, v164
	v_fma_f32 v166, -v216, v234, v195
	v_exp_f32_e32 v167, v160
	v_fma_f32 v160, -v215, v235, v188
	v_exp_f32_e32 v166, v166
	v_fma_f32 v186, -v216, v235, v196
	v_exp_f32_e32 v187, v160
	v_fma_f32 v160, -v215, v236, v189
	v_exp_f32_e32 v186, v186
	v_fma_f32 v188, -v216, v236, v197
	v_exp_f32_e32 v189, v160
	v_fma_f32 v160, -v215, v237, v190
	v_exp_f32_e32 v188, v188
	v_fma_f32 v190, -v216, v237, v198
	v_exp_f32_e32 v211, v160
	v_fma_f32 v160, -v215, v238, v191
	v_exp_f32_e32 v210, v190
	v_fma_f32 v190, -v216, v238, v199
	v_pk_add_f32 v[194:195], v[164:165], 0 op_sel_hi:[1,0]
	v_exp_f32_e32 v191, v160
	v_fma_f32 v160, -v215, v239, v192
	v_exp_f32_e32 v190, v190
	v_fma_f32 v192, -v216, v239, v200
	v_pk_add_f32 v[194:195], v[166:167], v[194:195]
	v_exp_f32_e32 v213, v160
	v_fma_f32 v160, -v215, v151, v193
	v_exp_f32_e32 v212, v192
	v_fma_f32 v192, -v216, v151, v201
	v_pk_add_f32 v[194:195], v[186:187], v[194:195]
	v_exp_f32_e32 v193, v160
	v_exp_f32_e32 v192, v192
	v_pk_add_f32 v[194:195], v[188:189], v[194:195]
	v_fma_f32 v152, -v218, v180, v152
	v_pk_add_f32 v[194:195], v[210:211], v[194:195]
	v_cvt_pk_bf16_f32 v164, v164, v166
	v_pk_add_f32 v[194:195], v[190:191], v[194:195]
	v_cvt_pk_bf16_f32 v166, v210, v190
	v_pk_add_f32 v[194:195], v[212:213], v[194:195]
	v_exp_f32_e32 v190, v152
	v_fma_f32 v152, -v218, v234, v153
	v_cvt_pk_bf16_f32 v160, v165, v167
	v_pk_add_f32 v[194:195], v[192:193], v[194:195]
	v_cvt_pk_bf16_f32 v165, v186, v188
	v_cvt_pk_bf16_f32 v167, v212, v192
	v_fma_f32 v186, -v217, v180, v202
	v_exp_f32_e32 v192, v152
	v_fma_f32 v152, -v218, v235, v154
	v_cvt_pk_bf16_f32 v162, v211, v191
	v_pk_add_f32 v[122:123], v[122:123], v[194:195]
	v_exp_f32_e32 v191, v186
	v_fma_f32 v186, -v217, v234, v203
	v_exp_f32_e32 v194, v152
	v_fma_f32 v152, -v218, v236, v155
	v_cvt_pk_bf16_f32 v163, v213, v193
	v_exp_f32_e32 v193, v186
	v_fma_f32 v186, -v217, v235, v204
	v_exp_f32_e32 v196, v152
	v_fma_f32 v152, -v218, v237, v156
	v_exp_f32_e32 v195, v186
	v_fma_f32 v186, -v217, v236, v205
	v_exp_f32_e32 v198, v152
	v_fma_f32 v152, -v218, v238, v157
	v_exp_f32_e32 v197, v186
	v_fma_f32 v186, -v217, v237, v206
	v_exp_f32_e32 v200, v152
	v_fma_f32 v152, -v218, v239, v158
	v_exp_f32_e32 v199, v186
	v_fma_f32 v186, -v217, v238, v207
	v_exp_f32_e32 v202, v152
	v_pk_add_f32 v[152:153], v[190:191], 0 op_sel_hi:[1,0]
	v_exp_f32_e32 v201, v186
	v_fma_f32 v186, -v217, v239, v208
	v_pk_add_f32 v[152:153], v[192:193], v[152:153]
	v_exp_f32_e32 v203, v186
	v_fma_f32 v186, -v217, v151, v209
	v_fma_f32 v151, -v218, v151, v159
	v_pk_add_f32 v[152:153], v[194:195], v[152:153]
	v_exp_f32_e32 v205, v186
	v_exp_f32_e32 v204, v151
	v_pk_add_f32 v[152:153], v[196:197], v[152:153]
	v_cvt_pk_bf16_f32 v161, v187, v189
	v_pk_add_f32 v[152:153], v[198:199], v[152:153]
	v_cvt_pk_bf16_f32 v186, v191, v193
	v_pk_add_f32 v[152:153], v[200:201], v[152:153]
	v_cvt_pk_bf16_f32 v187, v195, v197
	v_pk_add_f32 v[152:153], v[202:203], v[152:153]
	v_cvt_pk_bf16_f32 v188, v199, v201
	v_pk_add_f32 v[152:153], v[204:205], v[152:153]
	v_cvt_pk_bf16_f32 v189, v203, v205
	v_pk_add_f32 v[120:121], v[120:121], v[152:153]
	v_cvt_pk_bf16_f32 v152, v190, v192
	v_cvt_pk_bf16_f32 v153, v194, v196
	v_cvt_pk_bf16_f32 v154, v198, v200
	v_cvt_pk_bf16_f32 v155, v202, v204
	s_waitcnt lgkmcnt(3)
	v_mfma_f32_16x16x32_bf16 v[34:37], v[168:171], v[160:163], v[34:37]
	s_waitcnt lgkmcnt(2)
	v_mfma_f32_16x16x32_bf16 v[38:41], v[172:175], v[160:163], v[38:41]
	s_waitcnt lgkmcnt(1)
	v_mfma_f32_16x16x32_bf16 v[42:45], v[176:179], v[160:163], v[42:45]
	s_waitcnt lgkmcnt(0)
	v_mfma_f32_16x16x32_bf16 v[46:49], v[182:185], v[160:163], v[46:49]
	v_mfma_f32_16x16x32_bf16 v[50:53], v[168:171], v[164:167], v[50:53]
	v_mfma_f32_16x16x32_bf16 v[54:57], v[172:175], v[164:167], v[54:57]
	v_mfma_f32_16x16x32_bf16 v[58:61], v[176:179], v[164:167], v[58:61]
	v_mfma_f32_16x16x32_bf16 v[62:65], v[182:185], v[164:167], v[62:65]
	v_mfma_f32_16x16x32_bf16 v[66:69], v[168:171], v[186:189], v[66:69]
	v_mfma_f32_16x16x32_bf16 v[70:73], v[172:175], v[186:189], v[70:73]
	v_mfma_f32_16x16x32_bf16 v[74:77], v[176:179], v[186:189], v[74:77]
	v_mfma_f32_16x16x32_bf16 v[78:81], v[182:185], v[186:189], v[78:81]
	v_mfma_f32_16x16x32_bf16 v[82:85], v[168:171], v[152:155], v[82:85]
	v_mfma_f32_16x16x32_bf16 v[86:89], v[172:175], v[152:155], v[86:89]
	v_mfma_f32_16x16x32_bf16 v[90:93], v[176:179], v[152:155], v[90:93]
	v_mfma_f32_16x16x32_bf16 v[94:97], v[182:185], v[152:155], v[94:97]
	s_mov_b32 s20, 1
	s_and_b64 vcc, exec, s[18:19]
	s_mov_b64 s[18:19], 0
	s_cbranch_vccnz .LBB0_2689

.LBB0_2706:
	s_lshl_b32 s57, s52, 5
	s_or_b32 s53, s57, s16
	s_cmp_gt_i32 s53, s46
	s_cselect_b64 s[64:65], -1, 0
	s_or_b32 s59, s53, 31
	s_cmp_lt_i32 s59, s24
	s_cselect_b64 s[66:67], -1, 0
	s_or_b64 s[64:65], s[64:65], s[66:67]
	s_and_b64 vcc, exec, s[64:65]
	s_cbranch_vccnz .LBB0_2705
	v_or_b32_e32 v151, s57, v226
	v_mad_u32_u24 v151, v151, s49, v148
	ds_read_b128 v[152:155], v151
	ds_read_b128 v[156:159], v151 offset:64
	ds_read_b128 v[160:163], v151 offset:2304
	ds_read_b128 v[164:167], v151 offset:2368
	v_lshl_add_u32 v151, s52, 6, v150
	ds_read_b128 v[168:171], v151 offset:9216
	ds_read_b128 v[172:175], v151 offset:11520
	ds_read_b128 v[176:179], v151 offset:13824
	ds_read_b128 v[180:183], v151 offset:16128
	v_add_u32_e32 v151, s53, v144
	v_sub_u32_e32 v184, v227, v151
	v_cvt_f32_i32_e32 v185, v184
	v_xad_u32 v186, v151, -1, v227
	v_cvt_f32_i32_e32 v187, v186
	v_cmp_gt_u32_e32 vcc, s50, v184
	v_or_b32_e32 v184, 2, v151
	v_sub_u32_e32 v184, v227, v184
	v_cndmask_b32_e32 v212, v131, v185, vcc
	v_cmp_gt_u32_e32 vcc, s50, v186
	v_cvt_f32_i32_e32 v185, v184
	v_or_b32_e32 v186, 3, v151
	v_sub_u32_e32 v186, v227, v186
	v_cndmask_b32_e32 v213, v131, v187, vcc
	v_cvt_f32_i32_e32 v187, v186
	v_cmp_gt_u32_e32 vcc, s50, v184
	v_or_b32_e32 v184, 4, v151
	v_sub_u32_e32 v184, v227, v184
	v_cndmask_b32_e32 v224, v131, v185, vcc
	v_cvt_f32_i32_e32 v185, v184
	v_cmp_gt_u32_e32 vcc, s50, v186
	v_or_b32_e32 v186, 5, v151
	v_sub_u32_e32 v186, v227, v186
	v_cndmask_b32_e32 v225, v131, v187, vcc
	v_cmp_gt_u32_e32 vcc, s50, v184
	v_or_b32_e32 v184, 6, v151
	v_cvt_f32_i32_e32 v187, v186
	v_sub_u32_e32 v184, v227, v184
	v_or_b32_e32 v151, 7, v151
	v_cndmask_b32_e32 v228, v131, v185, vcc
	v_cvt_f32_i32_e32 v185, v184
	v_sub_u32_e32 v151, v227, v151
	v_cmp_gt_u32_e32 vcc, s50, v186
	v_cvt_f32_i32_e32 v186, v151
	s_nop 0
	v_cndmask_b32_e32 v229, v131, v187, vcc
	v_cmp_gt_u32_e32 vcc, s50, v184
	s_nop 1
	v_cndmask_b32_e32 v230, v131, v185, vcc
	v_cmp_gt_u32_e32 vcc, s50, v151
	s_nop 1
	v_cndmask_b32_e32 v151, v131, v186, vcc
	s_waitcnt lgkmcnt(7)
	v_mfma_f32_16x16x32_bf16 v[184:187], v[152:155], v[2:5], 0
	v_mfma_f32_16x16x32_bf16 v[192:195], v[152:155], v[10:13], 0
	v_mfma_f32_16x16x32_bf16 v[200:203], v[152:155], v[18:21], 0
	v_mfma_f32_16x16x32_bf16 v[152:155], v[152:155], v[26:29], 0
	s_waitcnt lgkmcnt(6)
	v_mfma_f32_16x16x32_bf16 v[184:187], v[156:159], v[6:9], v[184:187]
	s_waitcnt lgkmcnt(5)
	v_mfma_f32_16x16x32_bf16 v[188:191], v[160:163], v[2:5], 0
	v_mfma_f32_16x16x32_bf16 v[192:195], v[156:159], v[14:17], v[192:195]
	v_mfma_f32_16x16x32_bf16 v[196:199], v[160:163], v[10:13], 0
	v_mfma_f32_16x16x32_bf16 v[200:203], v[156:159], v[22:25], v[200:203]
	v_mfma_f32_16x16x32_bf16 v[204:207], v[160:163], v[18:21], 0
	v_mfma_f32_16x16x32_bf16 v[152:155], v[156:159], v[30:33], v[152:155]
	v_mfma_f32_16x16x32_bf16 v[156:159], v[160:163], v[26:29], 0
	s_waitcnt lgkmcnt(4)
	v_mfma_f32_16x16x32_bf16 v[188:191], v[164:167], v[6:9], v[188:191]
	v_mfma_f32_16x16x32_bf16 v[196:199], v[164:167], v[14:17], v[196:199]
	v_mfma_f32_16x16x32_bf16 v[204:207], v[164:167], v[22:25], v[204:207]
	v_mfma_f32_16x16x32_bf16 v[156:159], v[164:167], v[30:33], v[156:159]
	v_fma_f32 v160, -v215, v212, v184
	v_fma_f32 v164, -v216, v212, v192
	v_exp_f32_e32 v165, v160
	v_fma_f32 v160, -v215, v213, v185
	v_exp_f32_e32 v164, v164
	v_fma_f32 v166, -v216, v213, v193
	v_exp_f32_e32 v167, v160
	v_fma_f32 v160, -v215, v224, v186
	v_exp_f32_e32 v166, v166
	v_fma_f32 v184, -v216, v224, v194
	v_exp_f32_e32 v185, v160
	v_fma_f32 v160, -v215, v225, v187
	v_exp_f32_e32 v184, v184
	v_fma_f32 v186, -v216, v225, v195
	v_exp_f32_e32 v187, v160
	v_fma_f32 v160, -v215, v228, v188
	v_exp_f32_e32 v186, v186
	v_fma_f32 v188, -v216, v228, v196
	v_exp_f32_e32 v209, v160
	v_fma_f32 v160, -v215, v229, v189
	v_exp_f32_e32 v208, v188
	v_fma_f32 v188, -v216, v229, v197
	v_pk_add_f32 v[192:193], v[164:165], 0 op_sel_hi:[1,0]
	v_exp_f32_e32 v189, v160
	v_fma_f32 v160, -v215, v230, v190
	v_exp_f32_e32 v188, v188
	v_fma_f32 v190, -v216, v230, v198
	v_pk_add_f32 v[192:193], v[166:167], v[192:193]
	v_exp_f32_e32 v211, v160
	v_fma_f32 v160, -v215, v151, v191
	v_exp_f32_e32 v210, v190
	v_fma_f32 v190, -v216, v151, v199
	v_pk_add_f32 v[192:193], v[184:185], v[192:193]
	v_exp_f32_e32 v191, v160
	v_exp_f32_e32 v190, v190
	v_pk_add_f32 v[192:193], v[186:187], v[192:193]
	v_fma_f32 v152, -v218, v212, v152
	v_pk_add_f32 v[192:193], v[208:209], v[192:193]
	v_cvt_pk_bf16_f32 v164, v164, v166
	v_pk_add_f32 v[192:193], v[188:189], v[192:193]
	v_cvt_pk_bf16_f32 v166, v208, v188
	v_pk_add_f32 v[192:193], v[210:211], v[192:193]
	v_exp_f32_e32 v188, v152
	v_fma_f32 v152, -v218, v213, v153
	v_cvt_pk_bf16_f32 v160, v165, v167
	v_pk_add_f32 v[192:193], v[190:191], v[192:193]
	v_cvt_pk_bf16_f32 v165, v184, v186
	v_cvt_pk_bf16_f32 v167, v210, v190
	v_fma_f32 v184, -v217, v212, v200
	v_exp_f32_e32 v190, v152
	v_fma_f32 v152, -v218, v224, v154
	v_cvt_pk_bf16_f32 v162, v209, v189
	v_pk_add_f32 v[122:123], v[122:123], v[192:193]
	v_exp_f32_e32 v189, v184
	v_fma_f32 v184, -v217, v213, v201
	v_exp_f32_e32 v192, v152
	v_fma_f32 v152, -v218, v225, v155
	v_cvt_pk_bf16_f32 v163, v211, v191
	v_exp_f32_e32 v191, v184
	v_fma_f32 v184, -v217, v224, v202
	v_exp_f32_e32 v194, v152
	v_fma_f32 v152, -v218, v228, v156
	v_exp_f32_e32 v193, v184
	v_fma_f32 v184, -v217, v225, v203
	v_exp_f32_e32 v196, v152
	v_fma_f32 v152, -v218, v229, v157
	v_exp_f32_e32 v195, v184
	v_fma_f32 v184, -v217, v228, v204
	v_exp_f32_e32 v198, v152
	v_fma_f32 v152, -v218, v230, v158
	v_exp_f32_e32 v197, v184
	v_fma_f32 v184, -v217, v229, v205
	v_exp_f32_e32 v200, v152
	v_pk_add_f32 v[152:153], v[188:189], 0 op_sel_hi:[1,0]
	v_exp_f32_e32 v199, v184
	v_fma_f32 v184, -v217, v230, v206
	v_pk_add_f32 v[152:153], v[190:191], v[152:153]
	v_exp_f32_e32 v201, v184
	v_fma_f32 v184, -v217, v151, v207
	v_fma_f32 v151, -v218, v151, v159
	v_pk_add_f32 v[152:153], v[192:193], v[152:153]
	v_exp_f32_e32 v203, v184
	v_exp_f32_e32 v202, v151
	v_pk_add_f32 v[152:153], v[194:195], v[152:153]
	v_cvt_pk_bf16_f32 v161, v185, v187
	v_pk_add_f32 v[152:153], v[196:197], v[152:153]
	v_cvt_pk_bf16_f32 v184, v189, v191
	v_pk_add_f32 v[152:153], v[198:199], v[152:153]
	v_cvt_pk_bf16_f32 v185, v193, v195
	v_pk_add_f32 v[152:153], v[200:201], v[152:153]
	v_cvt_pk_bf16_f32 v186, v197, v199
	v_pk_add_f32 v[152:153], v[202:203], v[152:153]
	v_cvt_pk_bf16_f32 v187, v201, v203
	v_pk_add_f32 v[120:121], v[120:121], v[152:153]
	v_cvt_pk_bf16_f32 v152, v188, v190
	v_cvt_pk_bf16_f32 v153, v192, v194
	v_cvt_pk_bf16_f32 v154, v196, v198
	v_cvt_pk_bf16_f32 v155, v200, v202
	s_waitcnt lgkmcnt(3)
	v_mfma_f32_16x16x32_bf16 v[94:97], v[168:171], v[160:163], v[94:97]
	s_waitcnt lgkmcnt(2)
	v_mfma_f32_16x16x32_bf16 v[90:93], v[172:175], v[160:163], v[90:93]
	s_waitcnt lgkmcnt(1)
	v_mfma_f32_16x16x32_bf16 v[86:89], v[176:179], v[160:163], v[86:89]
	s_waitcnt lgkmcnt(0)
	v_mfma_f32_16x16x32_bf16 v[82:85], v[180:183], v[160:163], v[82:85]
	v_mfma_f32_16x16x32_bf16 v[78:81], v[168:171], v[164:167], v[78:81]
	v_mfma_f32_16x16x32_bf16 v[74:77], v[172:175], v[164:167], v[74:77]
	v_mfma_f32_16x16x32_bf16 v[70:73], v[176:179], v[164:167], v[70:73]
	v_mfma_f32_16x16x32_bf16 v[66:69], v[180:183], v[164:167], v[66:69]
	v_mfma_f32_16x16x32_bf16 v[62:65], v[168:171], v[184:187], v[62:65]
	v_mfma_f32_16x16x32_bf16 v[58:61], v[172:175], v[184:187], v[58:61]
	v_mfma_f32_16x16x32_bf16 v[54:57], v[176:179], v[184:187], v[54:57]
	v_mfma_f32_16x16x32_bf16 v[50:53], v[180:183], v[184:187], v[50:53]
	v_mfma_f32_16x16x32_bf16 v[46:49], v[168:171], v[152:155], v[46:49]
	v_mfma_f32_16x16x32_bf16 v[42:45], v[172:175], v[152:155], v[42:45]
	v_mfma_f32_16x16x32_bf16 v[38:41], v[176:179], v[152:155], v[38:41]
	v_mfma_f32_16x16x32_bf16 v[34:37], v[180:183], v[152:155], v[34:37]
	s_branch .LBB0_2705

.LBB0_2729:
	s_or_b32 s51, s52, s20
	s_lshl_b32 s53, s51, 4
	s_cmp_ge_i32 s53, s24
	s_cbranch_scc1 .LBB0_2728
	v_or_b32_e32 v57, s52, v226
	v_mad_u32_u24 v57, v57, s48, v46
	ds_read_b128 v[58:61], v57
	ds_read_b128 v[62:65], v57 offset:64
	ds_read_b128 v[66:69], v57 offset:2304
	ds_read_b128 v[70:73], v57 offset:2368
	v_subrev_u32_e32 v57, s51, v48
	v_lshl_add_u32 v57, v57, 4, v49
	v_cvt_f32_u32_e32 v74, v57
	v_xad_u32 v75, s51, -1, v48
	v_lshl_add_u32 v75, v75, 4, v49
	v_cvt_f32_u32_e32 v76, v75
	v_cmp_gt_u32_e32 vcc, 2.0, v57
	s_nop 1
	v_cndmask_b32_e32 v57, v56, v74, vcc
	v_subrev_u32_e32 v74, s51, v50
	v_cmp_gt_u32_e32 vcc, 2.0, v75
	v_lshl_add_u32 v74, v74, 4, v49
	v_cvt_f32_u32_e32 v75, v74
	v_cndmask_b32_e32 v98, v56, v76, vcc
	v_subrev_u32_e32 v76, s51, v51
	v_lshl_add_u32 v76, v76, 4, v49
	v_cvt_f32_u32_e32 v77, v76
	v_cmp_gt_u32_e32 vcc, 2.0, v74
	v_subrev_u32_e32 v74, s51, v52
	v_lshl_add_u32 v74, v74, 4, v49
	v_cndmask_b32_e32 v99, v56, v75, vcc
	v_cmp_gt_u32_e32 vcc, 2.0, v76
	v_cvt_f32_u32_e32 v75, v74
	v_subrev_u32_e32 v76, s51, v53
	v_lshl_add_u32 v76, v76, 4, v49
	v_cndmask_b32_e32 v100, v56, v77, vcc
	v_cvt_f32_u32_e32 v77, v76
	v_cmp_gt_u32_e32 vcc, 2.0, v74
	v_subrev_u32_e32 v74, s51, v54
	v_lshl_add_u32 v74, v74, 4, v49
	v_cndmask_b32_e32 v101, v56, v75, vcc
	v_cmp_gt_u32_e32 vcc, 2.0, v76
	v_subrev_u32_e32 v76, s51, v55
	v_cvt_f32_u32_e32 v75, v74
	v_lshl_add_u32 v76, v76, 4, v49
	v_cndmask_b32_e32 v102, v56, v77, vcc
	v_cvt_f32_u32_e32 v77, v76
	v_cmp_gt_u32_e32 vcc, 2.0, v74
	s_nop 1
	v_cndmask_b32_e32 v103, v56, v75, vcc
	v_cmp_gt_u32_e32 vcc, 2.0, v76
	s_nop 1
	v_cndmask_b32_e32 v104, v56, v77, vcc
	s_waitcnt vmcnt(7) lgkmcnt(3)
	v_mfma_f32_16x16x32_bf16 v[74:77], v[58:61], v[2:5], 0
	s_waitcnt vmcnt(5)
	v_mfma_f32_16x16x32_bf16 v[82:85], v[58:61], v[10:13], 0
	s_waitcnt vmcnt(3)
	v_mfma_f32_16x16x32_bf16 v[90:93], v[58:61], v[18:21], 0
	s_waitcnt vmcnt(1)
	v_mfma_f32_16x16x32_bf16 v[58:61], v[58:61], v[26:29], 0
	s_waitcnt lgkmcnt(2)
	v_mfma_f32_16x16x32_bf16 v[74:77], v[62:65], v[6:9], v[74:77]
	s_waitcnt lgkmcnt(1)
	v_mfma_f32_16x16x32_bf16 v[78:81], v[66:69], v[2:5], 0
	v_mfma_f32_16x16x32_bf16 v[82:85], v[62:65], v[14:17], v[82:85]
	v_mfma_f32_16x16x32_bf16 v[86:89], v[66:69], v[10:13], 0
	v_mfma_f32_16x16x32_bf16 v[90:93], v[62:65], v[22:25], v[90:93]
	v_mfma_f32_16x16x32_bf16 v[94:97], v[66:69], v[18:21], 0
	s_waitcnt vmcnt(0)
	v_mfma_f32_16x16x32_bf16 v[58:61], v[62:65], v[30:33], v[58:61]
	v_mfma_f32_16x16x32_bf16 v[62:65], v[66:69], v[26:29], 0
	s_waitcnt lgkmcnt(0)
	v_mfma_f32_16x16x32_bf16 v[78:81], v[70:73], v[6:9], v[78:81]
	v_mfma_f32_16x16x32_bf16 v[86:89], v[70:73], v[14:17], v[86:89]
	v_mfma_f32_16x16x32_bf16 v[94:97], v[70:73], v[22:25], v[94:97]
	v_mfma_f32_16x16x32_bf16 v[62:65], v[70:73], v[30:33], v[62:65]
	v_fma_f32 v66, -v215, v57, v74
	v_exp_f32_e32 v67, v66
	v_fma_f32 v66, -v215, v98, v75
	v_exp_f32_e32 v69, v66
	v_fma_f32 v66, -v215, v99, v76
	v_exp_f32_e32 v71, v66
	v_fma_f32 v66, -v215, v100, v77
	v_exp_f32_e32 v73, v66
	v_fma_f32 v66, -v215, v101, v78
	v_exp_f32_e32 v75, v66
	v_fma_f32 v66, -v215, v102, v79
	v_exp_f32_e32 v77, v66
	v_fma_f32 v66, -v215, v103, v80
	v_exp_f32_e32 v79, v66
	v_fma_f32 v66, -v215, v104, v81
	v_exp_f32_e32 v81, v66
	v_fma_f32 v66, -v216, v57, v82
	v_exp_f32_e32 v66, v66
	v_fma_f32 v68, -v216, v98, v83
	v_exp_f32_e32 v68, v68
	v_fma_f32 v70, -v216, v99, v84
	v_exp_f32_e32 v70, v70
	v_fma_f32 v72, -v216, v100, v85
	v_exp_f32_e32 v72, v72
	v_fma_f32 v74, -v216, v101, v86
	v_exp_f32_e32 v74, v74
	v_fma_f32 v76, -v216, v102, v87
	v_pk_add_f32 v[66:67], v[66:67], 0 op_sel_hi:[1,0]
	v_exp_f32_e32 v76, v76
	v_fma_f32 v78, -v216, v103, v88
	v_pk_add_f32 v[66:67], v[68:69], v[66:67]
	v_exp_f32_e32 v78, v78
	v_fma_f32 v80, -v216, v104, v89
	v_pk_add_f32 v[66:67], v[70:71], v[66:67]
	v_exp_f32_e32 v80, v80
	v_pk_add_f32 v[66:67], v[72:73], v[66:67]
	s_nop 0
	v_pk_add_f32 v[66:67], v[74:75], v[66:67]
	s_nop 0
	v_pk_add_f32 v[66:67], v[76:77], v[66:67]
	s_nop 0
	v_pk_add_f32 v[66:67], v[78:79], v[66:67]
	s_nop 0
	v_pk_add_f32 v[66:67], v[80:81], v[66:67]
	s_nop 0
	v_pk_add_f32 v[44:45], v[44:45], v[66:67]
	v_fma_f32 v66, -v217, v57, v90
	v_exp_f32_e32 v67, v66
	v_fma_f32 v66, -v217, v98, v91
	v_exp_f32_e32 v69, v66
	v_fma_f32 v66, -v217, v99, v92
	v_exp_f32_e32 v71, v66
	v_fma_f32 v66, -v217, v100, v93
	v_exp_f32_e32 v73, v66
	v_fma_f32 v66, -v217, v101, v94
	v_exp_f32_e32 v75, v66
	v_fma_f32 v66, -v217, v102, v95
	v_exp_f32_e32 v77, v66
	v_fma_f32 v66, -v217, v103, v96
	v_exp_f32_e32 v79, v66
	v_fma_f32 v66, -v217, v104, v97
	v_fma_f32 v57, -v218, v57, v58
	v_exp_f32_e32 v81, v66
	v_exp_f32_e32 v66, v57
	v_fma_f32 v57, -v218, v98, v59
	v_exp_f32_e32 v68, v57
	v_fma_f32 v57, -v218, v99, v60
	v_exp_f32_e32 v70, v57
	v_fma_f32 v57, -v218, v100, v61
	v_exp_f32_e32 v72, v57
	v_fma_f32 v57, -v218, v101, v62
	v_exp_f32_e32 v74, v57
	v_fma_f32 v57, -v218, v102, v63
	v_pk_add_f32 v[58:59], v[66:67], 0 op_sel_hi:[1,0]
	v_exp_f32_e32 v76, v57
	v_fma_f32 v57, -v218, v103, v64
	v_pk_add_f32 v[58:59], v[68:69], v[58:59]
	v_exp_f32_e32 v78, v57
	v_fma_f32 v57, -v218, v104, v65
	v_pk_add_f32 v[58:59], v[70:71], v[58:59]
	v_exp_f32_e32 v80, v57
	v_pk_add_f32 v[58:59], v[72:73], v[58:59]
	s_nop 0
	v_pk_add_f32 v[58:59], v[74:75], v[58:59]
	s_nop 0
	v_pk_add_f32 v[58:59], v[76:77], v[58:59]
	s_nop 0
	v_pk_add_f32 v[58:59], v[78:79], v[58:59]
	s_nop 0
	v_pk_add_f32 v[58:59], v[80:81], v[58:59]
	s_nop 0
	v_pk_add_f32 v[42:43], v[42:43], v[58:59]
	s_branch .LBB0_2728

.LBB0_2743:
	s_lshl_b32 s53, s52, 5
	s_or_b32 s51, s53, s16
	s_lshl_b32 s57, s51, 4
	s_cmp_ge_i32 s57, s24
	s_cbranch_scc1 .LBB0_2742
	v_subrev_u32_e32 v190, s51, v162
	v_lshl_add_u32 v190, v190, 4, v163
	v_cvt_f32_u32_e32 v191, v190
	v_xad_u32 v192, s51, -1, v162
	v_lshl_add_u32 v192, v192, 4, v163
	v_cvt_f32_u32_e32 v193, v192
	v_cmp_gt_u32_e32 vcc, 2.0, v190
	v_subrev_u32_e32 v190, s51, v164
	v_lshl_add_u32 v190, v190, 4, v163
	v_cndmask_b32_e32 v224, v172, v191, vcc
	v_cmp_gt_u32_e32 vcc, 2.0, v192
	v_cvt_f32_u32_e32 v191, v190
	v_subrev_u32_e32 v192, s51, v165
	v_lshl_add_u32 v192, v192, 4, v163
	v_cndmask_b32_e32 v225, v172, v193, vcc
	v_cvt_f32_u32_e32 v193, v192
	v_cmp_gt_u32_e32 vcc, 2.0, v190
	v_subrev_u32_e32 v190, s51, v166
	v_lshl_add_u32 v190, v190, 4, v163
	v_cndmask_b32_e32 v231, v172, v191, vcc
	v_cmp_gt_u32_e32 vcc, 2.0, v192
	v_cvt_f32_u32_e32 v191, v190
	v_subrev_u32_e32 v192, s51, v167
	v_or_b32_e32 v108, s53, v226
	v_lshl_add_u32 v192, v192, 4, v163
	v_mad_u32_u24 v108, v108, s48, v98
	v_lshl_add_u32 v120, s52, 6, v173
	v_cndmask_b32_e32 v232, v172, v193, vcc
	v_cvt_f32_u32_e32 v193, v192
	ds_read_b128 v[174:177], v108
	ds_read_b128 v[178:181], v108 offset:64
	ds_read_b128 v[182:185], v108 offset:2304
	ds_read_b128 v[186:189], v108 offset:2368
	ds_read_b128 v[108:111], v120 offset:9216
	ds_read_b128 v[112:115], v120 offset:11520
	ds_read_b128 v[116:119], v120 offset:13824
	ds_read_b128 v[120:123], v120 offset:16128
	v_cmp_gt_u32_e32 vcc, 2.0, v190
	v_subrev_u32_e32 v190, s51, v168
	v_lshl_add_u32 v190, v190, 4, v163
	v_cndmask_b32_e32 v233, v172, v191, vcc
	v_cmp_gt_u32_e32 vcc, 2.0, v192
	v_subrev_u32_e32 v192, s51, v169
	v_cvt_f32_u32_e32 v191, v190
	v_lshl_add_u32 v192, v192, 4, v163
	v_cndmask_b32_e32 v234, v172, v193, vcc
	v_cvt_f32_u32_e32 v193, v192
	v_cmp_gt_u32_e32 vcc, 2.0, v190
	s_nop 1
	v_cndmask_b32_e32 v235, v172, v191, vcc
	v_cmp_gt_u32_e32 vcc, 2.0, v192
	s_nop 1
	v_cndmask_b32_e32 v236, v172, v193, vcc
	s_waitcnt lgkmcnt(7)
	v_mfma_f32_16x16x32_bf16 v[190:193], v[174:177], v[2:5], 0
	v_mfma_f32_16x16x32_bf16 v[198:201], v[174:177], v[10:13], 0
	v_mfma_f32_16x16x32_bf16 v[206:209], v[174:177], v[18:21], 0
	v_mfma_f32_16x16x32_bf16 v[174:177], v[174:177], v[26:29], 0
	s_waitcnt lgkmcnt(6)
	v_mfma_f32_16x16x32_bf16 v[190:193], v[178:181], v[6:9], v[190:193]
	s_waitcnt lgkmcnt(5)
	v_mfma_f32_16x16x32_bf16 v[194:197], v[182:185], v[2:5], 0
	v_mfma_f32_16x16x32_bf16 v[198:201], v[178:181], v[14:17], v[198:201]
	v_mfma_f32_16x16x32_bf16 v[202:205], v[182:185], v[10:13], 0
	v_mfma_f32_16x16x32_bf16 v[206:209], v[178:181], v[22:25], v[206:209]
	v_mfma_f32_16x16x32_bf16 v[210:213], v[182:185], v[18:21], 0
	v_mfma_f32_16x16x32_bf16 v[174:177], v[178:181], v[30:33], v[174:177]
	v_mfma_f32_16x16x32_bf16 v[178:181], v[182:185], v[26:29], 0
	s_waitcnt lgkmcnt(4)
	v_mfma_f32_16x16x32_bf16 v[194:197], v[186:189], v[6:9], v[194:197]
	v_mfma_f32_16x16x32_bf16 v[202:205], v[186:189], v[14:17], v[202:205]
	v_mfma_f32_16x16x32_bf16 v[210:213], v[186:189], v[22:25], v[210:213]
	v_mfma_f32_16x16x32_bf16 v[178:181], v[186:189], v[30:33], v[178:181]
	v_fma_f32 v182, -v215, v224, v190
	v_fma_f32 v183, -v215, v225, v191
	v_fma_f32 v184, -v215, v231, v192
	v_fma_f32 v185, -v215, v232, v193
	v_exp_f32_e32 v182, v182
	v_exp_f32_e32 v183, v183
	v_exp_f32_e32 v184, v184
	v_exp_f32_e32 v185, v185
	v_fma_f32 v186, -v215, v233, v194
	v_fma_f32 v187, -v215, v234, v195
	v_fma_f32 v188, -v215, v235, v196
	v_fma_f32 v189, -v215, v236, v197
	v_exp_f32_e32 v186, v186
	v_exp_f32_e32 v187, v187
	v_exp_f32_e32 v188, v188
	v_exp_f32_e32 v189, v189
	v_pk_mul_f32 v[182:183], v[150:151], v[182:183]
	v_pk_mul_f32 v[184:185], v[150:151], v[184:185]
	v_add_f32_e32 v191, v182, v183
	v_add_f32_e32 v190, v184, v185
	v_pk_mul_f32 v[186:187], v[150:151], v[186:187]
	v_pk_mul_f32 v[188:189], v[150:151], v[188:189]
	v_add_f32_e32 v190, v191, v190
	v_add_f32_e32 v194, 0, v190
	v_add_f32_e32 v195, 0, v185
	v_add_f32_e32 v190, v188, v189
	v_add_f32_e32 v191, v186, v187
	v_add_f32_e32 v197, 0, v189
	v_cvt_pk_bf16_f32 v182, v182, v183
	v_cvt_pk_bf16_f32 v183, v184, v185
	v_cvt_pk_bf16_f32 v184, v186, v187
	v_cvt_pk_bf16_f32 v185, v188, v189
	v_fma_f32 v186, -v216, v224, v198
	v_fma_f32 v187, -v216, v225, v199
	v_fma_f32 v188, -v216, v231, v200
	v_fma_f32 v189, -v216, v232, v201
	v_add_f32_e32 v190, v191, v190
	v_exp_f32_e32 v186, v186
	v_exp_f32_e32 v187, v187
	v_exp_f32_e32 v188, v188
	v_exp_f32_e32 v189, v189
	v_add_f32_e32 v196, 0, v190
	v_fma_f32 v190, -v216, v233, v202
	v_fma_f32 v191, -v216, v234, v203
	v_fma_f32 v192, -v216, v235, v204
	v_fma_f32 v193, -v216, v236, v205
	v_exp_f32_e32 v190, v190
	v_exp_f32_e32 v191, v191
	v_exp_f32_e32 v192, v192
	v_exp_f32_e32 v193, v193
	v_pk_mul_f32 v[186:187], v[152:153], v[186:187]
	v_pk_mul_f32 v[188:189], v[152:153], v[188:189]
	v_add_f32_e32 v199, v186, v187
	v_add_f32_e32 v198, v188, v189
	v_pk_mul_f32 v[190:191], v[152:153], v[190:191]
	v_pk_mul_f32 v[192:193], v[152:153], v[192:193]
	v_add_f32_e32 v198, v199, v198
	v_add_f32_e32 v198, v194, v198
	v_add_f32_e32 v199, v195, v189
	v_add_f32_e32 v194, v192, v193
	v_add_f32_e32 v195, v190, v191
	v_add_f32_e32 v201, v197, v193
	v_cvt_pk_bf16_f32 v186, v186, v187
	v_cvt_pk_bf16_f32 v187, v188, v189
	v_cvt_pk_bf16_f32 v188, v190, v191
	v_cvt_pk_bf16_f32 v189, v192, v193
	v_fma_f32 v190, -v217, v224, v206
	v_fma_f32 v191, -v217, v225, v207
	v_fma_f32 v192, -v217, v231, v208
	v_fma_f32 v193, -v217, v232, v209
	v_add_f32_e32 v194, v195, v194
	v_exp_f32_e32 v190, v190
	v_exp_f32_e32 v191, v191
	v_exp_f32_e32 v192, v192
	v_exp_f32_e32 v193, v193
	v_add_f32_e32 v200, v196, v194
	v_fma_f32 v194, -v217, v233, v210
	v_fma_f32 v195, -v217, v234, v211
	v_fma_f32 v196, -v217, v235, v212
	v_fma_f32 v197, -v217, v236, v213
	v_exp_f32_e32 v194, v194
	v_exp_f32_e32 v195, v195
	v_exp_f32_e32 v196, v196
	v_exp_f32_e32 v197, v197
	v_fma_f32 v174, -v218, v224, v174
	v_fma_f32 v175, -v218, v225, v175
	v_fma_f32 v176, -v218, v231, v176
	v_fma_f32 v177, -v218, v232, v177
	v_fma_f32 v178, -v218, v233, v178
	v_fma_f32 v179, -v218, v234, v179
	v_fma_f32 v180, -v218, v235, v180
	v_fma_f32 v181, -v218, v236, v181
	v_exp_f32_e32 v174, v174
	v_exp_f32_e32 v175, v175
	v_exp_f32_e32 v176, v176
	v_exp_f32_e32 v177, v177
	v_exp_f32_e32 v178, v178
	v_exp_f32_e32 v179, v179
	v_exp_f32_e32 v180, v180
	v_exp_f32_e32 v181, v181
	v_pk_mul_f32 v[190:191], v[154:155], v[190:191]
	v_pk_mul_f32 v[192:193], v[154:155], v[192:193]
	v_add_f32_e32 v203, v190, v191
	v_add_f32_e32 v202, v192, v193
	v_pk_mul_f32 v[194:195], v[154:155], v[194:195]
	v_pk_mul_f32 v[196:197], v[154:155], v[196:197]
	v_add_f32_e32 v202, v203, v202
	v_add_f32_e32 v198, v198, v202
	v_add_f32_e32 v202, v196, v197
	v_add_f32_e32 v203, v194, v195
	v_pk_mul_f32 v[174:175], v[156:157], v[174:175]
	v_pk_mul_f32 v[176:177], v[156:157], v[176:177]
	v_pk_mul_f32 v[178:179], v[156:157], v[178:179]
	v_pk_mul_f32 v[180:181], v[156:157], v[180:181]
	v_add_f32_e32 v199, v199, v193
	v_add_f32_e32 v202, v203, v202
	v_add_f32_e32 v201, v201, v197
	v_cvt_pk_bf16_f32 v190, v190, v191
	v_cvt_pk_bf16_f32 v191, v192, v193
	v_cvt_pk_bf16_f32 v192, v194, v195
	v_cvt_pk_bf16_f32 v193, v196, v197
	v_add_f32_e32 v194, v176, v177
	v_add_f32_e32 v195, v174, v175
	v_add_f32_e32 v196, v180, v181
	v_add_f32_e32 v197, v178, v179
	v_add_f32_e32 v200, v200, v202
	v_add_f32_e32 v194, v195, v194
	v_add_f32_e32 v196, v197, v196
	v_add_f32_e32 v194, v198, v194
	v_add_f32_e32 v195, v199, v177
	v_add_f32_e32 v196, v200, v196
	v_add_f32_e32 v197, v201, v181
	v_cvt_pk_bf16_f32 v174, v174, v175
	v_cvt_pk_bf16_f32 v175, v176, v177
	v_cvt_pk_bf16_f32 v176, v178, v179
	v_cvt_pk_bf16_f32 v177, v180, v181
	s_waitcnt lgkmcnt(3)
	v_mfma_f32_16x16x32_bf16 v[94:97], v[108:111], v[182:185], v[94:97]
	s_waitcnt lgkmcnt(2)
	v_mfma_f32_16x16x32_bf16 v[90:93], v[112:115], v[182:185], v[90:93]
	s_waitcnt lgkmcnt(1)
	v_mfma_f32_16x16x32_bf16 v[86:89], v[116:119], v[182:185], v[86:89]
	s_waitcnt lgkmcnt(0)
	v_mfma_f32_16x16x32_bf16 v[82:85], v[120:123], v[182:185], v[82:85]
	v_mfma_f32_16x16x32_bf16 v[78:81], v[108:111], v[186:189], v[78:81]
	v_mfma_f32_16x16x32_bf16 v[74:77], v[112:115], v[186:189], v[74:77]
	v_mfma_f32_16x16x32_bf16 v[70:73], v[116:119], v[186:189], v[70:73]
	v_mfma_f32_16x16x32_bf16 v[66:69], v[120:123], v[186:189], v[66:69]
	v_mfma_f32_16x16x32_bf16 v[62:65], v[108:111], v[190:193], v[62:65]
	v_mfma_f32_16x16x32_bf16 v[58:61], v[112:115], v[190:193], v[58:61]
	v_mfma_f32_16x16x32_bf16 v[54:57], v[116:119], v[190:193], v[54:57]
	v_mfma_f32_16x16x32_bf16 v[50:53], v[120:123], v[190:193], v[50:53]
	v_mfma_f32_16x16x32_bf16 v[46:49], v[108:111], v[174:177], v[46:49]
	v_mfma_f32_16x16x32_bf16 v[42:45], v[112:115], v[174:177], v[42:45]
	v_mfma_f32_16x16x32_bf16 v[38:41], v[116:119], v[174:177], v[38:41]
	v_mfma_f32_16x16x32_bf16 v[34:37], v[120:123], v[174:177], v[34:37]
	v_add_u32_e32 v108, s51, v170
	ds_add_f32 v108, v194
	ds_add_f32 v108, v195 offset:4
	ds_add_f32 v108, v196 offset:4
	ds_add_f32 v108, v197 offset:8
	s_branch .LBB0_2742

.LBB0_2903:
	s_lshl_b32 s21, s20, 5
	v_or_b32_e32 v151, s21, v226
	v_mad_u32_u24 v151, v151, s46, v148
	ds_read_b128 v[152:155], v151
	ds_read_b128 v[156:159], v151 offset:64
	ds_read_b128 v[160:163], v151 offset:2304
	ds_read_b128 v[164:167], v151 offset:2368
	v_lshl_add_u32 v151, s20, 6, v149
	ds_read_b128 v[168:171], v151 offset:9216
	ds_read_b128 v[172:175], v151 offset:11520
	ds_read_b128 v[176:179], v151 offset:13824
	ds_read_b128 v[182:185], v151 offset:16128
	v_add_u32_e32 v151, s21, v150
	v_sub_u32_e32 v180, v227, v151
	v_cmp_gt_u32_e32 vcc, 2.0, v180
	v_cvt_f32_i32_e32 v180, v180
	v_xad_u32 v186, v151, -1, v227
	v_cvt_f32_i32_e32 v187, v186
	s_and_b64 vcc, s[16:17], vcc
	v_cndmask_b32_e32 v180, v236, v180, vcc
	v_cmp_gt_u32_e32 vcc, 2.0, v186
	v_or_b32_e32 v186, 2, v151
	s_and_b64 vcc, s[16:17], vcc
	v_sub_u32_e32 v186, v227, v186
	v_cndmask_b32_e32 v237, v236, v187, vcc
	v_cmp_gt_u32_e32 vcc, 2.0, v186
	v_cvt_f32_i32_e32 v186, v186
	v_or_b32_e32 v187, 3, v151
	v_sub_u32_e32 v187, v227, v187
	v_cvt_f32_i32_e32 v188, v187
	s_and_b64 vcc, s[16:17], vcc
	v_cndmask_b32_e32 v238, v236, v186, vcc
	v_cmp_gt_u32_e32 vcc, 2.0, v187
	v_or_b32_e32 v186, 4, v151
	s_and_b64 vcc, s[16:17], vcc
	v_sub_u32_e32 v186, v227, v186
	v_cndmask_b32_e32 v239, v236, v188, vcc
	v_cmp_gt_u32_e32 vcc, 2.0, v186
	v_cvt_f32_i32_e32 v186, v186
	v_or_b32_e32 v187, 5, v151
	v_sub_u32_e32 v187, v227, v187
	v_cvt_f32_i32_e32 v188, v187
	s_and_b64 vcc, s[16:17], vcc
	v_cndmask_b32_e32 v240, v236, v186, vcc
	v_cmp_gt_u32_e32 vcc, 2.0, v187
	v_or_b32_e32 v186, 6, v151
	s_and_b64 vcc, s[16:17], vcc
	v_sub_u32_e32 v186, v227, v186
	v_cndmask_b32_e32 v241, v236, v188, vcc
	v_cmp_gt_u32_e32 vcc, 2.0, v186
	v_cvt_f32_i32_e32 v186, v186
	v_or_b32_e32 v151, 7, v151
	v_sub_u32_e32 v151, v227, v151
	v_cvt_f32_i32_e32 v187, v151
	s_and_b64 vcc, s[16:17], vcc
	v_cndmask_b32_e32 v242, v236, v186, vcc
	v_cmp_gt_u32_e32 vcc, 2.0, v151
	s_and_b64 vcc, s[16:17], vcc
	s_nop 0
	v_cndmask_b32_e32 v151, v236, v187, vcc
	s_waitcnt lgkmcnt(7)
	v_mfma_f32_16x16x32_bf16 v[186:189], v[152:155], v[2:5], 0
	v_mfma_f32_16x16x32_bf16 v[194:197], v[152:155], v[10:13], 0
	v_mfma_f32_16x16x32_bf16 v[202:205], v[152:155], v[18:21], 0
	v_mfma_f32_16x16x32_bf16 v[152:155], v[152:155], v[26:29], 0
	s_waitcnt lgkmcnt(6)
	v_mfma_f32_16x16x32_bf16 v[186:189], v[156:159], v[6:9], v[186:189]
	s_waitcnt lgkmcnt(5)
	v_mfma_f32_16x16x32_bf16 v[190:193], v[160:163], v[2:5], 0
	v_mfma_f32_16x16x32_bf16 v[194:197], v[156:159], v[14:17], v[194:197]
	v_mfma_f32_16x16x32_bf16 v[198:201], v[160:163], v[10:13], 0
	v_mfma_f32_16x16x32_bf16 v[202:205], v[156:159], v[22:25], v[202:205]
	v_mfma_f32_16x16x32_bf16 v[206:209], v[160:163], v[18:21], 0
	v_mfma_f32_16x16x32_bf16 v[152:155], v[156:159], v[30:33], v[152:155]
	v_mfma_f32_16x16x32_bf16 v[156:159], v[160:163], v[26:29], 0
	s_waitcnt lgkmcnt(4)
	v_mfma_f32_16x16x32_bf16 v[190:193], v[164:167], v[6:9], v[190:193]
	v_mfma_f32_16x16x32_bf16 v[198:201], v[164:167], v[14:17], v[198:201]
	v_mfma_f32_16x16x32_bf16 v[206:209], v[164:167], v[22:25], v[206:209]
	v_mfma_f32_16x16x32_bf16 v[156:159], v[164:167], v[30:33], v[156:159]
	v_fma_f32 v160, -v215, v180, v186
	v_fma_f32 v164, -v216, v180, v194
	v_exp_f32_e32 v165, v160
	v_fma_f32 v160, -v215, v237, v187
	v_exp_f32_e32 v164, v164
	v_fma_f32 v166, -v216, v237, v195
	v_exp_f32_e32 v167, v160
	v_fma_f32 v160, -v215, v238, v188
	v_exp_f32_e32 v166, v166
	v_fma_f32 v186, -v216, v238, v196
	v_exp_f32_e32 v187, v160
	v_fma_f32 v160, -v215, v239, v189
	v_exp_f32_e32 v186, v186
	v_fma_f32 v188, -v216, v239, v197
	v_exp_f32_e32 v189, v160
	v_fma_f32 v160, -v215, v240, v190
	v_exp_f32_e32 v188, v188
	v_fma_f32 v190, -v216, v240, v198
	v_exp_f32_e32 v211, v160
	v_fma_f32 v160, -v215, v241, v191
	v_exp_f32_e32 v210, v190
	v_fma_f32 v190, -v216, v241, v199
	v_pk_add_f32 v[194:195], v[164:165], 0 op_sel_hi:[1,0]
	v_exp_f32_e32 v191, v160
	v_fma_f32 v160, -v215, v242, v192
	v_exp_f32_e32 v190, v190
	v_fma_f32 v192, -v216, v242, v200
	v_pk_add_f32 v[194:195], v[166:167], v[194:195]
	v_exp_f32_e32 v213, v160
	v_fma_f32 v160, -v215, v151, v193
	v_exp_f32_e32 v212, v192
	v_fma_f32 v192, -v216, v151, v201
	v_pk_add_f32 v[194:195], v[186:187], v[194:195]
	v_exp_f32_e32 v193, v160
	v_exp_f32_e32 v192, v192
	v_pk_add_f32 v[194:195], v[188:189], v[194:195]
	v_fma_f32 v152, -v218, v180, v152
	v_pk_add_f32 v[194:195], v[210:211], v[194:195]
	v_cvt_pk_bf16_f32 v164, v164, v166
	v_pk_add_f32 v[194:195], v[190:191], v[194:195]
	v_cvt_pk_bf16_f32 v166, v210, v190
	v_pk_add_f32 v[194:195], v[212:213], v[194:195]
	v_exp_f32_e32 v190, v152
	v_fma_f32 v152, -v218, v237, v153
	v_cvt_pk_bf16_f32 v160, v165, v167
	v_pk_add_f32 v[194:195], v[192:193], v[194:195]
	v_cvt_pk_bf16_f32 v165, v186, v188
	v_cvt_pk_bf16_f32 v167, v212, v192
	v_fma_f32 v186, -v217, v180, v202
	v_exp_f32_e32 v192, v152
	v_fma_f32 v152, -v218, v238, v154
	v_cvt_pk_bf16_f32 v162, v211, v191
	v_pk_add_f32 v[122:123], v[122:123], v[194:195]
	v_exp_f32_e32 v191, v186
	v_fma_f32 v186, -v217, v237, v203
	v_exp_f32_e32 v194, v152
	v_fma_f32 v152, -v218, v239, v155
	v_cvt_pk_bf16_f32 v163, v213, v193
	v_exp_f32_e32 v193, v186
	v_fma_f32 v186, -v217, v238, v204
	v_exp_f32_e32 v196, v152
	v_fma_f32 v152, -v218, v240, v156
	v_exp_f32_e32 v195, v186
	v_fma_f32 v186, -v217, v239, v205
	v_exp_f32_e32 v198, v152
	v_fma_f32 v152, -v218, v241, v157
	v_exp_f32_e32 v197, v186
	v_fma_f32 v186, -v217, v240, v206
	v_exp_f32_e32 v200, v152
	v_fma_f32 v152, -v218, v242, v158
	v_exp_f32_e32 v199, v186
	v_fma_f32 v186, -v217, v241, v207
	v_exp_f32_e32 v202, v152
	v_pk_add_f32 v[152:153], v[190:191], 0 op_sel_hi:[1,0]
	v_exp_f32_e32 v201, v186
	v_fma_f32 v186, -v217, v242, v208
	v_pk_add_f32 v[152:153], v[192:193], v[152:153]
	v_exp_f32_e32 v203, v186
	v_fma_f32 v186, -v217, v151, v209
	v_fma_f32 v151, -v218, v151, v159
	v_pk_add_f32 v[152:153], v[194:195], v[152:153]
	v_exp_f32_e32 v205, v186
	v_exp_f32_e32 v204, v151
	v_pk_add_f32 v[152:153], v[196:197], v[152:153]
	v_cvt_pk_bf16_f32 v161, v187, v189
	v_pk_add_f32 v[152:153], v[198:199], v[152:153]
	v_cvt_pk_bf16_f32 v186, v191, v193
	v_pk_add_f32 v[152:153], v[200:201], v[152:153]
	v_cvt_pk_bf16_f32 v187, v195, v197
	v_pk_add_f32 v[152:153], v[202:203], v[152:153]
	v_cvt_pk_bf16_f32 v188, v199, v201
	v_pk_add_f32 v[152:153], v[204:205], v[152:153]
	v_cvt_pk_bf16_f32 v189, v203, v205
	v_pk_add_f32 v[120:121], v[120:121], v[152:153]
	v_cvt_pk_bf16_f32 v152, v190, v192
	v_cvt_pk_bf16_f32 v153, v194, v196
	v_cvt_pk_bf16_f32 v154, v198, v200
	v_cvt_pk_bf16_f32 v155, v202, v204
	s_waitcnt lgkmcnt(3)
	v_mfma_f32_16x16x32_bf16 v[34:37], v[168:171], v[160:163], v[34:37]
	s_waitcnt lgkmcnt(2)
	v_mfma_f32_16x16x32_bf16 v[38:41], v[172:175], v[160:163], v[38:41]
	s_waitcnt lgkmcnt(1)
	v_mfma_f32_16x16x32_bf16 v[42:45], v[176:179], v[160:163], v[42:45]
	s_waitcnt lgkmcnt(0)
	v_mfma_f32_16x16x32_bf16 v[46:49], v[182:185], v[160:163], v[46:49]
	v_mfma_f32_16x16x32_bf16 v[50:53], v[168:171], v[164:167], v[50:53]
	v_mfma_f32_16x16x32_bf16 v[54:57], v[172:175], v[164:167], v[54:57]
	v_mfma_f32_16x16x32_bf16 v[58:61], v[176:179], v[164:167], v[58:61]
	v_mfma_f32_16x16x32_bf16 v[62:65], v[182:185], v[164:167], v[62:65]
	v_mfma_f32_16x16x32_bf16 v[66:69], v[168:171], v[186:189], v[66:69]
	v_mfma_f32_16x16x32_bf16 v[70:73], v[172:175], v[186:189], v[70:73]
	v_mfma_f32_16x16x32_bf16 v[74:77], v[176:179], v[186:189], v[74:77]
	v_mfma_f32_16x16x32_bf16 v[78:81], v[182:185], v[186:189], v[78:81]
	v_mfma_f32_16x16x32_bf16 v[82:85], v[168:171], v[152:155], v[82:85]
	v_mfma_f32_16x16x32_bf16 v[86:89], v[172:175], v[152:155], v[86:89]
	v_mfma_f32_16x16x32_bf16 v[90:93], v[176:179], v[152:155], v[90:93]
	v_mfma_f32_16x16x32_bf16 v[94:97], v[182:185], v[152:155], v[94:97]
	s_mov_b32 s20, 1
	s_and_b64 vcc, exec, s[18:19]
	s_mov_b64 s[18:19], 0
	s_cbranch_vccnz .LBB0_2903

.LBB0_2920:
	s_lshl_b32 s49, s47, 5
	s_or_b32 s48, s49, s16
	s_cmp_gt_i32 s48, s41
	s_cselect_b64 s[50:51], -1, 0
	s_or_b32 s52, s48, 31
	s_cmp_lt_i32 s52, s24
	s_cselect_b64 s[52:53], -1, 0
	s_or_b64 s[50:51], s[50:51], s[52:53]
	s_and_b64 vcc, exec, s[50:51]
	s_cbranch_vccnz .LBB0_2919
	v_add_u32_e32 v184, s48, v144
	v_sub_u32_e32 v185, v227, v184
	v_cvt_f32_i32_e32 v186, v185
	v_xad_u32 v187, v184, -1, v227
	v_cvt_f32_i32_e32 v188, v187
	v_cmp_gt_u32_e32 vcc, s45, v185
	v_or_b32_e32 v185, 2, v184
	v_sub_u32_e32 v185, v227, v185
	v_cndmask_b32_e32 v212, v150, v186, vcc
	v_cmp_gt_u32_e32 vcc, s45, v187
	v_cvt_f32_i32_e32 v186, v185
	v_or_b32_e32 v187, 3, v184
	v_sub_u32_e32 v187, v227, v187
	v_cndmask_b32_e32 v213, v150, v188, vcc
	v_cvt_f32_i32_e32 v188, v187
	v_cmp_gt_u32_e32 vcc, s45, v185
	v_or_b32_e32 v185, 4, v184
	v_sub_u32_e32 v185, v227, v185
	v_or_b32_e32 v152, s49, v226
	v_cndmask_b32_e32 v228, v150, v186, vcc
	v_cvt_f32_i32_e32 v186, v185
	v_mad_u32_u24 v164, v152, s43, v148
	v_lshl_add_u32 v180, s47, 6, v151
	v_cmp_gt_u32_e32 vcc, s45, v187
	v_or_b32_e32 v187, 5, v184
	ds_read_b128 v[152:155], v164
	ds_read_b128 v[156:159], v164 offset:64
	ds_read_b128 v[160:163], v164 offset:2304
	ds_read_b128 v[164:167], v164 offset:2368
	ds_read_b128 v[168:171], v180 offset:9216
	ds_read_b128 v[172:175], v180 offset:11520
	ds_read_b128 v[176:179], v180 offset:13824
	ds_read_b128 v[180:183], v180 offset:16128
	v_cndmask_b32_e32 v229, v150, v188, vcc
	v_sub_u32_e32 v187, v227, v187
	v_cmp_gt_u32_e32 vcc, s45, v185
	v_or_b32_e32 v185, 6, v184
	v_cvt_f32_i32_e32 v188, v187
	v_sub_u32_e32 v185, v227, v185
	v_or_b32_e32 v184, 7, v184
	v_cndmask_b32_e32 v230, v150, v186, vcc
	v_cvt_f32_i32_e32 v186, v185
	v_sub_u32_e32 v184, v227, v184
	v_cmp_gt_u32_e32 vcc, s45, v187
	v_cvt_f32_i32_e32 v187, v184
	s_nop 0
	v_cndmask_b32_e32 v231, v150, v188, vcc
	v_cmp_gt_u32_e32 vcc, s45, v185
	s_nop 1
	v_cndmask_b32_e32 v232, v150, v186, vcc
	v_cmp_gt_u32_e32 vcc, s45, v184
	s_nop 1
	v_cndmask_b32_e32 v233, v150, v187, vcc
	s_waitcnt lgkmcnt(7)
	v_mfma_f32_16x16x32_bf16 v[184:187], v[152:155], v[2:5], 0
	v_mfma_f32_16x16x32_bf16 v[192:195], v[152:155], v[10:13], 0
	v_mfma_f32_16x16x32_bf16 v[200:203], v[152:155], v[18:21], 0
	v_mfma_f32_16x16x32_bf16 v[152:155], v[152:155], v[26:29], 0
	s_waitcnt lgkmcnt(6)
	v_mfma_f32_16x16x32_bf16 v[184:187], v[156:159], v[6:9], v[184:187]
	s_waitcnt lgkmcnt(5)
	v_mfma_f32_16x16x32_bf16 v[188:191], v[160:163], v[2:5], 0
	v_mfma_f32_16x16x32_bf16 v[192:195], v[156:159], v[14:17], v[192:195]
	v_mfma_f32_16x16x32_bf16 v[196:199], v[160:163], v[10:13], 0
	v_mfma_f32_16x16x32_bf16 v[200:203], v[156:159], v[22:25], v[200:203]
	v_mfma_f32_16x16x32_bf16 v[204:207], v[160:163], v[18:21], 0
	v_mfma_f32_16x16x32_bf16 v[152:155], v[156:159], v[30:33], v[152:155]
	v_mfma_f32_16x16x32_bf16 v[156:159], v[160:163], v[26:29], 0
	s_waitcnt lgkmcnt(4)
	v_mfma_f32_16x16x32_bf16 v[188:191], v[164:167], v[6:9], v[188:191]
	v_mfma_f32_16x16x32_bf16 v[196:199], v[164:167], v[14:17], v[196:199]
	v_mfma_f32_16x16x32_bf16 v[204:207], v[164:167], v[22:25], v[204:207]
	v_mfma_f32_16x16x32_bf16 v[156:159], v[164:167], v[30:33], v[156:159]
	v_fma_f32 v160, -v215, v212, v184
	v_fma_f32 v164, -v216, v212, v192
	v_exp_f32_e32 v165, v160
	v_fma_f32 v160, -v215, v213, v185
	v_exp_f32_e32 v164, v164
	v_fma_f32 v166, -v216, v213, v193
	v_exp_f32_e32 v167, v160
	v_fma_f32 v160, -v215, v228, v186
	v_exp_f32_e32 v166, v166
	v_fma_f32 v184, -v216, v228, v194
	v_exp_f32_e32 v185, v160
	v_fma_f32 v160, -v215, v229, v187
	v_exp_f32_e32 v184, v184
	v_fma_f32 v186, -v216, v229, v195
	v_exp_f32_e32 v187, v160
	v_fma_f32 v160, -v215, v230, v188
	v_exp_f32_e32 v186, v186
	v_fma_f32 v188, -v216, v230, v196
	v_exp_f32_e32 v209, v160
	v_fma_f32 v160, -v215, v231, v189
	v_exp_f32_e32 v208, v188
	v_fma_f32 v188, -v216, v231, v197
	v_pk_add_f32 v[192:193], v[164:165], 0 op_sel_hi:[1,0]
	v_exp_f32_e32 v189, v160
	v_fma_f32 v160, -v215, v232, v190
	v_exp_f32_e32 v188, v188
	v_fma_f32 v190, -v216, v232, v198
	v_pk_add_f32 v[192:193], v[166:167], v[192:193]
	v_exp_f32_e32 v211, v160
	v_fma_f32 v160, -v215, v233, v191
	v_exp_f32_e32 v210, v190
	v_fma_f32 v190, -v216, v233, v199
	v_pk_add_f32 v[192:193], v[184:185], v[192:193]
	v_exp_f32_e32 v191, v160
	v_exp_f32_e32 v190, v190
	v_pk_add_f32 v[192:193], v[186:187], v[192:193]
	v_fma_f32 v152, -v218, v212, v152
	v_pk_add_f32 v[192:193], v[208:209], v[192:193]
	v_cvt_pk_bf16_f32 v164, v164, v166
	v_pk_add_f32 v[192:193], v[188:189], v[192:193]
	v_cvt_pk_bf16_f32 v166, v208, v188
	v_pk_add_f32 v[192:193], v[210:211], v[192:193]
	v_exp_f32_e32 v188, v152
	v_fma_f32 v152, -v218, v213, v153
	v_cvt_pk_bf16_f32 v160, v165, v167
	v_pk_add_f32 v[192:193], v[190:191], v[192:193]
	v_cvt_pk_bf16_f32 v167, v210, v190
	v_exp_f32_e32 v190, v152
	v_fma_f32 v152, -v218, v228, v154
	v_pk_add_f32 v[122:123], v[122:123], v[192:193]
	v_cvt_pk_bf16_f32 v165, v184, v186
	v_fma_f32 v184, -v217, v212, v200
	v_exp_f32_e32 v192, v152
	v_fma_f32 v152, -v218, v229, v155
	v_cvt_pk_bf16_f32 v162, v209, v189
	v_exp_f32_e32 v189, v184
	v_fma_f32 v184, -v217, v213, v201
	v_exp_f32_e32 v194, v152
	v_fma_f32 v152, -v218, v230, v156
	v_cvt_pk_bf16_f32 v163, v211, v191
	v_exp_f32_e32 v191, v184
	v_fma_f32 v184, -v217, v228, v202
	v_exp_f32_e32 v196, v152
	v_fma_f32 v152, -v218, v231, v157
	v_exp_f32_e32 v193, v184
	v_fma_f32 v184, -v217, v229, v203
	v_exp_f32_e32 v198, v152
	v_fma_f32 v152, -v218, v232, v158
	v_exp_f32_e32 v195, v184
	v_fma_f32 v184, -v217, v230, v204
	v_exp_f32_e32 v200, v152
	v_fma_f32 v152, -v218, v233, v159
	v_exp_f32_e32 v197, v184
	v_fma_f32 v184, -v217, v231, v205
	v_exp_f32_e32 v202, v152
	v_pk_add_f32 v[152:153], v[188:189], 0 op_sel_hi:[1,0]
	v_exp_f32_e32 v199, v184
	v_fma_f32 v184, -v217, v232, v206
	v_pk_add_f32 v[152:153], v[190:191], v[152:153]
	v_exp_f32_e32 v201, v184
	v_fma_f32 v184, -v217, v233, v207
	v_pk_add_f32 v[152:153], v[192:193], v[152:153]
	v_exp_f32_e32 v203, v184
	v_pk_add_f32 v[152:153], v[194:195], v[152:153]
	v_cvt_pk_bf16_f32 v161, v185, v187
	v_pk_add_f32 v[152:153], v[196:197], v[152:153]
	v_cvt_pk_bf16_f32 v184, v189, v191
	v_pk_add_f32 v[152:153], v[198:199], v[152:153]
	v_cvt_pk_bf16_f32 v185, v193, v195
	v_pk_add_f32 v[152:153], v[200:201], v[152:153]
	v_cvt_pk_bf16_f32 v186, v197, v199
	v_pk_add_f32 v[152:153], v[202:203], v[152:153]
	v_cvt_pk_bf16_f32 v187, v201, v203
	v_pk_add_f32 v[120:121], v[120:121], v[152:153]
	v_cvt_pk_bf16_f32 v152, v188, v190
	v_cvt_pk_bf16_f32 v153, v192, v194
	v_cvt_pk_bf16_f32 v154, v196, v198
	v_cvt_pk_bf16_f32 v155, v200, v202
	s_waitcnt lgkmcnt(3)
	v_mfma_f32_16x16x32_bf16 v[94:97], v[168:171], v[160:163], v[94:97]
	s_waitcnt lgkmcnt(2)
	v_mfma_f32_16x16x32_bf16 v[90:93], v[172:175], v[160:163], v[90:93]
	s_waitcnt lgkmcnt(1)
	v_mfma_f32_16x16x32_bf16 v[86:89], v[176:179], v[160:163], v[86:89]
	s_waitcnt lgkmcnt(0)
	v_mfma_f32_16x16x32_bf16 v[82:85], v[180:183], v[160:163], v[82:85]
	v_mfma_f32_16x16x32_bf16 v[78:81], v[168:171], v[164:167], v[78:81]
	v_mfma_f32_16x16x32_bf16 v[74:77], v[172:175], v[164:167], v[74:77]
	v_mfma_f32_16x16x32_bf16 v[70:73], v[176:179], v[164:167], v[70:73]
	v_mfma_f32_16x16x32_bf16 v[66:69], v[180:183], v[164:167], v[66:69]
	v_mfma_f32_16x16x32_bf16 v[62:65], v[168:171], v[184:187], v[62:65]
	v_mfma_f32_16x16x32_bf16 v[58:61], v[172:175], v[184:187], v[58:61]
	v_mfma_f32_16x16x32_bf16 v[54:57], v[176:179], v[184:187], v[54:57]
	v_mfma_f32_16x16x32_bf16 v[50:53], v[180:183], v[184:187], v[50:53]
	v_mfma_f32_16x16x32_bf16 v[46:49], v[168:171], v[152:155], v[46:49]
	v_mfma_f32_16x16x32_bf16 v[42:45], v[172:175], v[152:155], v[42:45]
	v_mfma_f32_16x16x32_bf16 v[38:41], v[176:179], v[152:155], v[38:41]
	v_mfma_f32_16x16x32_bf16 v[34:37], v[180:183], v[152:155], v[34:37]
	s_branch .LBB0_2919

.LBB0_2938:
	s_or_b32 s41, s42, s14
	s_lshl_b32 s43, s41, 4
	s_cmp_ge_i32 s43, s3
	s_cbranch_scc1 .LBB0_2937
	v_or_b32_e32 v49, s42, v208
	v_mad_u32_u24 v49, v49, s20, v44
	ds_read_b128 v[50:53], v49
	ds_read_b128 v[54:57], v49 offset:64
	ds_read_b128 v[58:61], v49 offset:2304
	ds_read_b128 v[62:65], v49 offset:2368
	v_subrev_u32_e32 v49, s41, v1
	v_lshl_add_u32 v49, v49, 4, v160
	v_cvt_f32_u32_e32 v66, v49
	v_xad_u32 v67, s41, -1, v1
	v_lshl_add_u32 v67, v67, 4, v160
	v_cvt_f32_u32_e32 v68, v67
	v_cmp_gt_u32_e32 vcc, 2.0, v49
	s_nop 1
	v_cndmask_b32_e32 v49, v48, v66, vcc
	v_subrev_u32_e32 v66, s41, v161
	v_cmp_gt_u32_e32 vcc, 2.0, v67
	v_lshl_add_u32 v66, v66, 4, v160
	v_cvt_f32_u32_e32 v67, v66
	v_cndmask_b32_e32 v90, v48, v68, vcc
	v_subrev_u32_e32 v68, s41, v162
	v_lshl_add_u32 v68, v68, 4, v160
	v_cvt_f32_u32_e32 v69, v68
	v_cmp_gt_u32_e32 vcc, 2.0, v66
	v_subrev_u32_e32 v66, s41, v163
	v_lshl_add_u32 v66, v66, 4, v160
	v_cndmask_b32_e32 v91, v48, v67, vcc
	v_cmp_gt_u32_e32 vcc, 2.0, v68
	v_cvt_f32_u32_e32 v67, v66
	v_subrev_u32_e32 v68, s41, v164
	v_lshl_add_u32 v68, v68, 4, v160
	v_cndmask_b32_e32 v92, v48, v69, vcc
	v_cvt_f32_u32_e32 v69, v68
	v_cmp_gt_u32_e32 vcc, 2.0, v66
	v_subrev_u32_e32 v66, s41, v165
	v_lshl_add_u32 v66, v66, 4, v160
	v_cndmask_b32_e32 v93, v48, v67, vcc
	v_cmp_gt_u32_e32 vcc, 2.0, v68
	v_subrev_u32_e32 v68, s41, v166
	v_cvt_f32_u32_e32 v67, v66
	v_lshl_add_u32 v68, v68, 4, v160
	v_cndmask_b32_e32 v94, v48, v69, vcc
	v_cvt_f32_u32_e32 v69, v68
	v_cmp_gt_u32_e32 vcc, 2.0, v66
	s_nop 1
	v_cndmask_b32_e32 v95, v48, v67, vcc
	v_cmp_gt_u32_e32 vcc, 2.0, v68
	s_nop 1
	v_cndmask_b32_e32 v96, v48, v69, vcc
	s_waitcnt lgkmcnt(3)
	v_mfma_f32_16x16x32_bf16 v[66:69], v[50:53], v[2:5], 0
	v_mfma_f32_16x16x32_bf16 v[74:77], v[50:53], v[10:13], 0
	v_mfma_f32_16x16x32_bf16 v[82:85], v[50:53], v[18:21], 0
	v_mfma_f32_16x16x32_bf16 v[50:53], v[50:53], v[26:29], 0
	s_waitcnt lgkmcnt(2)
	v_mfma_f32_16x16x32_bf16 v[66:69], v[54:57], v[6:9], v[66:69]
	s_waitcnt lgkmcnt(1)
	v_mfma_f32_16x16x32_bf16 v[70:73], v[58:61], v[2:5], 0
	v_mfma_f32_16x16x32_bf16 v[74:77], v[54:57], v[14:17], v[74:77]
	v_mfma_f32_16x16x32_bf16 v[78:81], v[58:61], v[10:13], 0
	v_mfma_f32_16x16x32_bf16 v[82:85], v[54:57], v[22:25], v[82:85]
	v_mfma_f32_16x16x32_bf16 v[86:89], v[58:61], v[18:21], 0
	v_mfma_f32_16x16x32_bf16 v[50:53], v[54:57], v[30:33], v[50:53]
	v_mfma_f32_16x16x32_bf16 v[54:57], v[58:61], v[26:29], 0
	s_waitcnt lgkmcnt(0)
	v_mfma_f32_16x16x32_bf16 v[70:73], v[62:65], v[6:9], v[70:73]
	v_mfma_f32_16x16x32_bf16 v[78:81], v[62:65], v[14:17], v[78:81]
	v_mfma_f32_16x16x32_bf16 v[86:89], v[62:65], v[22:25], v[86:89]
	v_mfma_f32_16x16x32_bf16 v[54:57], v[62:65], v[30:33], v[54:57]
	v_fma_f32 v58, -v215, v49, v66
	v_exp_f32_e32 v59, v58
	v_fma_f32 v58, -v215, v90, v67
	v_exp_f32_e32 v61, v58
	v_fma_f32 v58, -v215, v91, v68
	v_exp_f32_e32 v63, v58
	v_fma_f32 v58, -v215, v92, v69
	v_exp_f32_e32 v65, v58
	v_fma_f32 v58, -v215, v93, v70
	v_exp_f32_e32 v67, v58
	v_fma_f32 v58, -v215, v94, v71
	v_exp_f32_e32 v69, v58
	v_fma_f32 v58, -v215, v95, v72
	v_exp_f32_e32 v71, v58
	v_fma_f32 v58, -v215, v96, v73
	v_exp_f32_e32 v73, v58
	v_fma_f32 v58, -v216, v49, v74
	v_exp_f32_e32 v58, v58
	v_fma_f32 v60, -v216, v90, v75
	v_exp_f32_e32 v60, v60
	v_fma_f32 v62, -v216, v91, v76
	v_exp_f32_e32 v62, v62
	v_fma_f32 v64, -v216, v92, v77
	v_exp_f32_e32 v64, v64
	v_fma_f32 v66, -v216, v93, v78
	v_exp_f32_e32 v66, v66
	v_fma_f32 v68, -v216, v94, v79
	v_pk_add_f32 v[58:59], v[58:59], 0 op_sel_hi:[1,0]
	v_exp_f32_e32 v68, v68
	v_fma_f32 v70, -v216, v95, v80
	v_pk_add_f32 v[58:59], v[60:61], v[58:59]
	v_exp_f32_e32 v70, v70
	v_fma_f32 v72, -v216, v96, v81
	v_pk_add_f32 v[58:59], v[62:63], v[58:59]
	v_exp_f32_e32 v72, v72
	v_pk_add_f32 v[58:59], v[64:65], v[58:59]
	s_nop 0
	v_pk_add_f32 v[58:59], v[66:67], v[58:59]
	s_nop 0
	v_pk_add_f32 v[58:59], v[68:69], v[58:59]
	s_nop 0
	v_pk_add_f32 v[58:59], v[70:71], v[58:59]
	s_nop 0
	v_pk_add_f32 v[58:59], v[72:73], v[58:59]
	s_nop 0
	v_pk_add_f32 v[46:47], v[46:47], v[58:59]
	v_fma_f32 v58, -v217, v49, v82
	v_exp_f32_e32 v59, v58
	v_fma_f32 v58, -v217, v90, v83
	v_exp_f32_e32 v61, v58
	v_fma_f32 v58, -v217, v91, v84
	v_exp_f32_e32 v63, v58
	v_fma_f32 v58, -v217, v92, v85
	v_exp_f32_e32 v65, v58
	v_fma_f32 v58, -v217, v93, v86
	v_exp_f32_e32 v67, v58
	v_fma_f32 v58, -v217, v94, v87
	v_exp_f32_e32 v69, v58
	v_fma_f32 v58, -v217, v95, v88
	v_exp_f32_e32 v71, v58
	v_fma_f32 v58, -v217, v96, v89
	v_fma_f32 v49, -v218, v49, v50
	v_exp_f32_e32 v73, v58
	v_exp_f32_e32 v58, v49
	v_fma_f32 v49, -v218, v90, v51
	v_exp_f32_e32 v60, v49
	v_fma_f32 v49, -v218, v91, v52
	v_exp_f32_e32 v62, v49
	v_fma_f32 v49, -v218, v92, v53
	v_exp_f32_e32 v64, v49
	v_fma_f32 v49, -v218, v93, v54
	v_exp_f32_e32 v66, v49
	v_fma_f32 v49, -v218, v94, v55
	v_pk_add_f32 v[50:51], v[58:59], 0 op_sel_hi:[1,0]
	v_exp_f32_e32 v68, v49
	v_fma_f32 v49, -v218, v95, v56
	v_pk_add_f32 v[50:51], v[60:61], v[50:51]
	v_exp_f32_e32 v70, v49
	v_fma_f32 v49, -v218, v96, v57
	v_pk_add_f32 v[50:51], v[62:63], v[50:51]
	v_exp_f32_e32 v72, v49
	v_pk_add_f32 v[50:51], v[64:65], v[50:51]
	s_nop 0
	v_pk_add_f32 v[50:51], v[66:67], v[50:51]
	s_nop 0
	v_pk_add_f32 v[50:51], v[68:69], v[50:51]
	s_nop 0
	v_pk_add_f32 v[50:51], v[70:71], v[50:51]
	s_nop 0
	v_pk_add_f32 v[50:51], v[72:73], v[50:51]
	s_nop 0
	v_pk_add_f32 v[42:43], v[42:43], v[50:51]
	s_branch .LBB0_2937

.LBB0_2949:
	s_lshl_b32 s43, s42, 5
	s_or_b32 s41, s43, s20
	s_lshl_b32 s45, s41, 4
	s_cmp_ge_i32 s45, s3
	s_cbranch_scc1 .LBB0_2948
	v_subrev_u32_e32 v186, s41, v1
	v_lshl_add_u32 v186, v186, 4, v160
	v_cvt_f32_u32_e32 v187, v186
	v_xad_u32 v188, s41, -1, v1
	v_lshl_add_u32 v188, v188, 4, v160
	v_cvt_f32_u32_e32 v189, v188
	v_cmp_gt_u32_e32 vcc, 2.0, v186
	v_subrev_u32_e32 v186, s41, v161
	v_lshl_add_u32 v186, v186, 4, v160
	v_cndmask_b32_e32 v206, v168, v187, vcc
	v_cmp_gt_u32_e32 vcc, 2.0, v188
	v_cvt_f32_u32_e32 v187, v186
	v_subrev_u32_e32 v188, s41, v162
	v_lshl_add_u32 v188, v188, 4, v160
	v_cndmask_b32_e32 v207, v168, v189, vcc
	v_cvt_f32_u32_e32 v189, v188
	v_cmp_gt_u32_e32 vcc, 2.0, v186
	v_subrev_u32_e32 v186, s41, v163
	v_lshl_add_u32 v186, v186, 4, v160
	v_cndmask_b32_e32 v230, v168, v187, vcc
	v_cmp_gt_u32_e32 vcc, 2.0, v188
	v_cvt_f32_u32_e32 v187, v186
	v_subrev_u32_e32 v188, s41, v164
	v_or_b32_e32 v108, s43, v208
	v_lshl_add_u32 v188, v188, 4, v160
	v_mad_u32_u24 v108, v108, s18, v98
	v_lshl_add_u32 v120, s42, 6, v169
	v_cndmask_b32_e32 v231, v168, v189, vcc
	v_cvt_f32_u32_e32 v189, v188
	ds_read_b128 v[170:173], v108
	ds_read_b128 v[174:177], v108 offset:64
	ds_read_b128 v[178:181], v108 offset:2304
	ds_read_b128 v[182:185], v108 offset:2368
	ds_read_b128 v[108:111], v120 offset:9216
	ds_read_b128 v[112:115], v120 offset:11520
	ds_read_b128 v[116:119], v120 offset:13824
	ds_read_b128 v[120:123], v120 offset:16128
	v_cmp_gt_u32_e32 vcc, 2.0, v186
	v_subrev_u32_e32 v186, s41, v165
	v_lshl_add_u32 v186, v186, 4, v160
	v_cndmask_b32_e32 v232, v168, v187, vcc
	v_cmp_gt_u32_e32 vcc, 2.0, v188
	v_subrev_u32_e32 v188, s41, v166
	v_cvt_f32_u32_e32 v187, v186
	v_lshl_add_u32 v188, v188, 4, v160
	v_cndmask_b32_e32 v233, v168, v189, vcc
	v_cvt_f32_u32_e32 v189, v188
	v_cmp_gt_u32_e32 vcc, 2.0, v186
	s_nop 1
	v_cndmask_b32_e32 v234, v168, v187, vcc
	v_cmp_gt_u32_e32 vcc, 2.0, v188
	s_nop 1
	v_cndmask_b32_e32 v235, v168, v189, vcc
	s_waitcnt lgkmcnt(7)
	v_mfma_f32_16x16x32_bf16 v[186:189], v[170:173], v[2:5], 0
	v_mfma_f32_16x16x32_bf16 v[194:197], v[170:173], v[10:13], 0
	v_mfma_f32_16x16x32_bf16 v[202:205], v[170:173], v[18:21], 0
	v_mfma_f32_16x16x32_bf16 v[170:173], v[170:173], v[26:29], 0
	s_waitcnt lgkmcnt(6)
	v_mfma_f32_16x16x32_bf16 v[186:189], v[174:177], v[6:9], v[186:189]
	s_waitcnt lgkmcnt(5)
	v_mfma_f32_16x16x32_bf16 v[190:193], v[178:181], v[2:5], 0
	v_mfma_f32_16x16x32_bf16 v[194:197], v[174:177], v[14:17], v[194:197]
	v_mfma_f32_16x16x32_bf16 v[198:201], v[178:181], v[10:13], 0
	v_mfma_f32_16x16x32_bf16 v[202:205], v[174:177], v[22:25], v[202:205]
	v_mfma_f32_16x16x32_bf16 v[226:229], v[178:181], v[18:21], 0
	v_mfma_f32_16x16x32_bf16 v[170:173], v[174:177], v[30:33], v[170:173]
	v_mfma_f32_16x16x32_bf16 v[174:177], v[178:181], v[26:29], 0
	s_waitcnt lgkmcnt(4)
	v_mfma_f32_16x16x32_bf16 v[190:193], v[182:185], v[6:9], v[190:193]
	v_mfma_f32_16x16x32_bf16 v[198:201], v[182:185], v[14:17], v[198:201]
	v_mfma_f32_16x16x32_bf16 v[226:229], v[182:185], v[22:25], v[226:229]
	v_mfma_f32_16x16x32_bf16 v[174:177], v[182:185], v[30:33], v[174:177]
	v_fma_f32 v178, -v215, v206, v186
	v_fma_f32 v179, -v215, v207, v187
	v_fma_f32 v180, -v215, v230, v188
	v_fma_f32 v181, -v215, v231, v189
	v_exp_f32_e32 v178, v178
	v_exp_f32_e32 v179, v179
	v_exp_f32_e32 v180, v180
	v_exp_f32_e32 v181, v181
	v_fma_f32 v182, -v215, v232, v190
	v_fma_f32 v183, -v215, v233, v191
	v_fma_f32 v184, -v215, v234, v192
	v_fma_f32 v185, -v215, v235, v193
	v_exp_f32_e32 v182, v182
	v_exp_f32_e32 v183, v183
	v_exp_f32_e32 v184, v184
	v_exp_f32_e32 v185, v185
	v_pk_mul_f32 v[178:179], v[142:143], v[178:179]
	v_pk_mul_f32 v[180:181], v[142:143], v[180:181]
	v_add_f32_e32 v187, v178, v179
	v_add_f32_e32 v186, v180, v181
	v_pk_mul_f32 v[182:183], v[142:143], v[182:183]
	v_pk_mul_f32 v[184:185], v[142:143], v[184:185]
	v_add_f32_e32 v186, v187, v186
	v_add_f32_e32 v190, 0, v186
	v_add_f32_e32 v191, 0, v181
	v_add_f32_e32 v186, v184, v185
	v_add_f32_e32 v187, v182, v183
	v_add_f32_e32 v193, 0, v185
	v_cvt_pk_bf16_f32 v178, v178, v179
	v_cvt_pk_bf16_f32 v179, v180, v181
	v_cvt_pk_bf16_f32 v180, v182, v183
	v_cvt_pk_bf16_f32 v181, v184, v185
	v_fma_f32 v182, -v216, v206, v194
	v_fma_f32 v183, -v216, v207, v195
	v_fma_f32 v184, -v216, v230, v196
	v_fma_f32 v185, -v216, v231, v197
	v_add_f32_e32 v186, v187, v186
	v_exp_f32_e32 v182, v182
	v_exp_f32_e32 v183, v183
	v_exp_f32_e32 v184, v184
	v_exp_f32_e32 v185, v185
	v_add_f32_e32 v192, 0, v186
	v_fma_f32 v186, -v216, v232, v198
	v_fma_f32 v187, -v216, v233, v199
	v_fma_f32 v188, -v216, v234, v200
	v_fma_f32 v189, -v216, v235, v201
	v_exp_f32_e32 v186, v186
	v_exp_f32_e32 v187, v187
	v_exp_f32_e32 v188, v188
	v_exp_f32_e32 v189, v189
	v_pk_mul_f32 v[182:183], v[150:151], v[182:183]
	v_pk_mul_f32 v[184:185], v[150:151], v[184:185]
	v_add_f32_e32 v195, v182, v183
	v_add_f32_e32 v194, v184, v185
	v_pk_mul_f32 v[186:187], v[150:151], v[186:187]
	v_pk_mul_f32 v[188:189], v[150:151], v[188:189]
	v_add_f32_e32 v194, v195, v194
	v_add_f32_e32 v194, v190, v194
	v_add_f32_e32 v195, v191, v185
	v_add_f32_e32 v190, v188, v189
	v_add_f32_e32 v191, v186, v187
	v_add_f32_e32 v197, v193, v189
	v_cvt_pk_bf16_f32 v182, v182, v183
	v_cvt_pk_bf16_f32 v183, v184, v185
	v_cvt_pk_bf16_f32 v184, v186, v187
	v_cvt_pk_bf16_f32 v185, v188, v189
	v_fma_f32 v186, -v217, v206, v202
	v_fma_f32 v187, -v217, v207, v203
	v_fma_f32 v188, -v217, v230, v204
	v_fma_f32 v189, -v217, v231, v205
	v_add_f32_e32 v190, v191, v190
	v_exp_f32_e32 v186, v186
	v_exp_f32_e32 v187, v187
	v_exp_f32_e32 v188, v188
	v_exp_f32_e32 v189, v189
	v_add_f32_e32 v196, v192, v190
	v_fma_f32 v190, -v217, v232, v226
	v_fma_f32 v191, -v217, v233, v227
	v_fma_f32 v192, -v217, v234, v228
	v_fma_f32 v193, -v217, v235, v229
	v_exp_f32_e32 v190, v190
	v_exp_f32_e32 v191, v191
	v_exp_f32_e32 v192, v192
	v_exp_f32_e32 v193, v193
	v_fma_f32 v170, -v218, v206, v170
	v_fma_f32 v171, -v218, v207, v171
	v_fma_f32 v172, -v218, v230, v172
	v_fma_f32 v173, -v218, v231, v173
	v_fma_f32 v174, -v218, v232, v174
	v_fma_f32 v175, -v218, v233, v175
	v_fma_f32 v176, -v218, v234, v176
	v_fma_f32 v177, -v218, v235, v177
	v_exp_f32_e32 v170, v170
	v_exp_f32_e32 v171, v171
	v_exp_f32_e32 v172, v172
	v_exp_f32_e32 v173, v173
	v_exp_f32_e32 v174, v174
	v_exp_f32_e32 v175, v175
	v_exp_f32_e32 v176, v176
	v_exp_f32_e32 v177, v177
	v_pk_mul_f32 v[186:187], v[152:153], v[186:187]
	v_pk_mul_f32 v[188:189], v[152:153], v[188:189]
	v_add_f32_e32 v199, v186, v187
	v_add_f32_e32 v198, v188, v189
	v_pk_mul_f32 v[190:191], v[152:153], v[190:191]
	v_pk_mul_f32 v[192:193], v[152:153], v[192:193]
	v_add_f32_e32 v198, v199, v198
	v_add_f32_e32 v194, v194, v198
	v_add_f32_e32 v198, v192, v193
	v_add_f32_e32 v199, v190, v191
	v_pk_mul_f32 v[170:171], v[154:155], v[170:171]
	v_pk_mul_f32 v[172:173], v[154:155], v[172:173]
	v_pk_mul_f32 v[174:175], v[154:155], v[174:175]
	v_pk_mul_f32 v[176:177], v[154:155], v[176:177]
	v_add_f32_e32 v195, v195, v189
	v_add_f32_e32 v198, v199, v198
	v_add_f32_e32 v197, v197, v193
	v_cvt_pk_bf16_f32 v186, v186, v187
	v_cvt_pk_bf16_f32 v187, v188, v189
	v_cvt_pk_bf16_f32 v188, v190, v191
	v_cvt_pk_bf16_f32 v189, v192, v193
	v_add_f32_e32 v190, v172, v173
	v_add_f32_e32 v191, v170, v171
	v_add_f32_e32 v192, v176, v177
	v_add_f32_e32 v193, v174, v175
	v_add_f32_e32 v196, v196, v198
	v_add_f32_e32 v190, v191, v190
	v_add_f32_e32 v192, v193, v192
	v_add_f32_e32 v190, v194, v190
	v_add_f32_e32 v191, v195, v173
	v_add_f32_e32 v192, v196, v192
	v_add_f32_e32 v193, v197, v177
	v_cvt_pk_bf16_f32 v170, v170, v171
	v_cvt_pk_bf16_f32 v171, v172, v173
	v_cvt_pk_bf16_f32 v172, v174, v175
	v_cvt_pk_bf16_f32 v173, v176, v177
	s_waitcnt lgkmcnt(3)
	v_mfma_f32_16x16x32_bf16 v[94:97], v[108:111], v[178:181], v[94:97]
	s_waitcnt lgkmcnt(2)
	v_mfma_f32_16x16x32_bf16 v[90:93], v[112:115], v[178:181], v[90:93]
	s_waitcnt lgkmcnt(1)
	v_mfma_f32_16x16x32_bf16 v[86:89], v[116:119], v[178:181], v[86:89]
	s_waitcnt lgkmcnt(0)
	v_mfma_f32_16x16x32_bf16 v[82:85], v[120:123], v[178:181], v[82:85]
	v_mfma_f32_16x16x32_bf16 v[78:81], v[108:111], v[182:185], v[78:81]
	v_mfma_f32_16x16x32_bf16 v[74:77], v[112:115], v[182:185], v[74:77]
	v_mfma_f32_16x16x32_bf16 v[70:73], v[116:119], v[182:185], v[70:73]
	v_mfma_f32_16x16x32_bf16 v[66:69], v[120:123], v[182:185], v[66:69]
	v_mfma_f32_16x16x32_bf16 v[62:65], v[108:111], v[186:189], v[62:65]
	v_mfma_f32_16x16x32_bf16 v[58:61], v[112:115], v[186:189], v[58:61]
	v_mfma_f32_16x16x32_bf16 v[54:57], v[116:119], v[186:189], v[54:57]
	v_mfma_f32_16x16x32_bf16 v[50:53], v[120:123], v[186:189], v[50:53]
	v_mfma_f32_16x16x32_bf16 v[46:49], v[108:111], v[170:173], v[46:49]
	v_mfma_f32_16x16x32_bf16 v[42:45], v[112:115], v[170:173], v[42:45]
	v_mfma_f32_16x16x32_bf16 v[38:41], v[116:119], v[170:173], v[38:41]
	v_mfma_f32_16x16x32_bf16 v[34:37], v[120:123], v[170:173], v[34:37]
	v_add_u32_e32 v108, s41, v167
	ds_add_f32 v108, v190
	ds_add_f32 v108, v191 offset:4
	ds_add_f32 v108, v192 offset:4
	ds_add_f32 v108, v193 offset:8
	s_branch .LBB0_2948

.LBB0_3106:
	s_lshl_b32 s7, s6, 5
	v_or_b32_e32 v141, s7, v208
	v_mad_u32_u24 v141, v141, s13, v138
	ds_read_b128 v[148:151], v141
	ds_read_b128 v[152:155], v141 offset:64
	ds_read_b128 v[156:159], v141 offset:2304
	ds_read_b128 v[160:163], v141 offset:2368
	v_lshl_add_u32 v141, s6, 6, v139
	ds_read_b128 v[164:167], v141 offset:9216
	ds_read_b128 v[168:171], v141 offset:11520
	ds_read_b128 v[176:179], v141 offset:13824
	ds_read_b128 v[180:183], v141 offset:16128
	v_add_u32_e32 v141, s7, v140
	v_sub_u32_e32 v142, v209, v141
	v_cmp_gt_u32_e32 vcc, 2.0, v142
	v_cvt_f32_i32_e32 v142, v142
	v_xad_u32 v143, v141, -1, v209
	v_cvt_f32_i32_e32 v172, v143
	s_and_b64 vcc, s[0:1], vcc
	v_cndmask_b32_e32 v174, v222, v142, vcc
	v_cmp_gt_u32_e32 vcc, 2.0, v143
	v_or_b32_e32 v142, 2, v141
	s_and_b64 vcc, s[0:1], vcc
	v_sub_u32_e32 v142, v209, v142
	v_cndmask_b32_e32 v223, v222, v172, vcc
	v_cmp_gt_u32_e32 vcc, 2.0, v142
	v_cvt_f32_i32_e32 v142, v142
	v_or_b32_e32 v143, 3, v141
	v_sub_u32_e32 v143, v209, v143
	v_cvt_f32_i32_e32 v172, v143
	s_and_b64 vcc, s[0:1], vcc
	v_cndmask_b32_e32 v226, v222, v142, vcc
	v_cmp_gt_u32_e32 vcc, 2.0, v143
	v_or_b32_e32 v142, 4, v141
	s_and_b64 vcc, s[0:1], vcc
	v_sub_u32_e32 v142, v209, v142
	v_cndmask_b32_e32 v227, v222, v172, vcc
	v_cmp_gt_u32_e32 vcc, 2.0, v142
	v_cvt_f32_i32_e32 v142, v142
	v_or_b32_e32 v143, 5, v141
	v_sub_u32_e32 v143, v209, v143
	v_cvt_f32_i32_e32 v172, v143
	s_and_b64 vcc, s[0:1], vcc
	v_cndmask_b32_e32 v228, v222, v142, vcc
	v_cmp_gt_u32_e32 vcc, 2.0, v143
	v_or_b32_e32 v142, 6, v141
	s_and_b64 vcc, s[0:1], vcc
	v_sub_u32_e32 v142, v209, v142
	v_cndmask_b32_e32 v229, v222, v172, vcc
	v_cmp_gt_u32_e32 vcc, 2.0, v142
	v_cvt_f32_i32_e32 v142, v142
	v_or_b32_e32 v141, 7, v141
	v_sub_u32_e32 v141, v209, v141
	v_cvt_f32_i32_e32 v143, v141
	s_and_b64 vcc, s[0:1], vcc
	v_cndmask_b32_e32 v230, v222, v142, vcc
	v_cmp_gt_u32_e32 vcc, 2.0, v141
	s_and_b64 vcc, s[0:1], vcc
	s_nop 0
	v_cndmask_b32_e32 v141, v222, v143, vcc
	s_waitcnt lgkmcnt(7)
	v_mfma_f32_16x16x32_bf16 v[184:187], v[148:151], v[2:5], 0
	v_mfma_f32_16x16x32_bf16 v[192:195], v[148:151], v[10:13], 0
	v_mfma_f32_16x16x32_bf16 v[200:203], v[148:151], v[18:21], 0
	v_mfma_f32_16x16x32_bf16 v[148:151], v[148:151], v[26:29], 0
	s_waitcnt lgkmcnt(6)
	v_mfma_f32_16x16x32_bf16 v[184:187], v[152:155], v[6:9], v[184:187]
	s_waitcnt lgkmcnt(5)
	v_mfma_f32_16x16x32_bf16 v[188:191], v[156:159], v[2:5], 0
	v_mfma_f32_16x16x32_bf16 v[192:195], v[152:155], v[14:17], v[192:195]
	v_mfma_f32_16x16x32_bf16 v[196:199], v[156:159], v[10:13], 0
	v_mfma_f32_16x16x32_bf16 v[200:203], v[152:155], v[22:25], v[200:203]
	v_mfma_f32_16x16x32_bf16 v[204:207], v[156:159], v[18:21], 0
	v_mfma_f32_16x16x32_bf16 v[148:151], v[152:155], v[30:33], v[148:151]
	v_mfma_f32_16x16x32_bf16 v[152:155], v[156:159], v[26:29], 0
	s_waitcnt lgkmcnt(4)
	v_mfma_f32_16x16x32_bf16 v[188:191], v[160:163], v[6:9], v[188:191]
	v_mfma_f32_16x16x32_bf16 v[196:199], v[160:163], v[14:17], v[196:199]
	v_mfma_f32_16x16x32_bf16 v[204:207], v[160:163], v[22:25], v[204:207]
	v_mfma_f32_16x16x32_bf16 v[152:155], v[160:163], v[30:33], v[152:155]
	v_fma_f32 v142, -v215, v174, v184
	v_exp_f32_e32 v143, v142
	v_fma_f32 v142, -v215, v223, v185
	v_exp_f32_e32 v161, v142
	v_fma_f32 v142, -v215, v226, v186
	v_exp_f32_e32 v163, v142
	v_fma_f32 v142, -v215, v227, v187
	v_exp_f32_e32 v173, v142
	v_fma_f32 v142, -v215, v228, v188
	v_exp_f32_e32 v185, v142
	v_fma_f32 v142, -v215, v229, v189
	v_exp_f32_e32 v187, v142
	v_fma_f32 v142, -v215, v230, v190
	v_exp_f32_e32 v189, v142
	v_fma_f32 v142, -v215, v141, v191
	v_exp_f32_e32 v191, v142
	v_fma_f32 v142, -v216, v174, v192
	v_exp_f32_e32 v142, v142
	v_fma_f32 v160, -v216, v223, v193
	v_exp_f32_e32 v160, v160
	v_fma_f32 v162, -v216, v226, v194
	v_exp_f32_e32 v162, v162
	v_fma_f32 v172, -v216, v227, v195
	v_exp_f32_e32 v172, v172
	v_fma_f32 v184, -v216, v228, v196
	v_exp_f32_e32 v184, v184
	v_fma_f32 v186, -v216, v229, v197
	v_pk_add_f32 v[192:193], v[142:143], 0 op_sel_hi:[1,0]
	v_exp_f32_e32 v186, v186
	v_fma_f32 v188, -v216, v230, v198
	v_pk_add_f32 v[192:193], v[160:161], v[192:193]
	v_exp_f32_e32 v188, v188
	v_fma_f32 v190, -v216, v141, v199
	v_pk_add_f32 v[192:193], v[162:163], v[192:193]
	v_exp_f32_e32 v190, v190
	v_pk_add_f32 v[192:193], v[172:173], v[192:193]
	v_cvt_pk_bf16_f32 v160, v142, v160
	v_fma_f32 v142, -v217, v174, v200
	v_cvt_pk_bf16_f32 v156, v143, v161
	v_pk_add_f32 v[192:193], v[184:185], v[192:193]
	v_exp_f32_e32 v143, v142
	v_fma_f32 v142, -v217, v223, v201
	v_cvt_pk_bf16_f32 v157, v163, v173
	v_pk_add_f32 v[192:193], v[186:187], v[192:193]
	v_exp_f32_e32 v173, v142
	v_fma_f32 v142, -v217, v226, v202
	v_cvt_pk_bf16_f32 v159, v189, v191
	v_pk_add_f32 v[192:193], v[188:189], v[192:193]
	v_exp_f32_e32 v189, v142
	v_fma_f32 v142, -v217, v227, v203
	v_pk_add_f32 v[192:193], v[190:191], v[192:193]
	v_exp_f32_e32 v191, v142
	v_fma_f32 v142, -v217, v228, v204
	v_pk_add_f32 v[122:123], v[122:123], v[192:193]
	v_exp_f32_e32 v193, v142
	v_fma_f32 v142, -v217, v229, v205
	v_exp_f32_e32 v195, v142
	v_fma_f32 v142, -v217, v230, v206
	v_exp_f32_e32 v197, v142
	v_fma_f32 v142, -v217, v141, v207
	v_exp_f32_e32 v199, v142
	v_fma_f32 v142, -v218, v174, v148
	v_fma_f32 v148, -v218, v223, v149
	v_cvt_pk_bf16_f32 v161, v162, v172
	v_exp_f32_e32 v172, v148
	v_fma_f32 v148, -v218, v226, v150
	v_cvt_pk_bf16_f32 v163, v188, v190
	v_exp_f32_e32 v142, v142
	v_exp_f32_e32 v188, v148
	v_fma_f32 v148, -v218, v227, v151
	v_exp_f32_e32 v190, v148
	v_fma_f32 v148, -v218, v228, v152
	v_exp_f32_e32 v192, v148
	v_fma_f32 v148, -v218, v229, v153
	v_exp_f32_e32 v194, v148
	v_fma_f32 v148, -v218, v230, v154
	v_exp_f32_e32 v196, v148
	v_pk_add_f32 v[148:149], v[142:143], 0 op_sel_hi:[1,0]
	v_fma_f32 v141, -v218, v141, v155
	v_pk_add_f32 v[148:149], v[172:173], v[148:149]
	v_exp_f32_e32 v198, v141
	v_pk_add_f32 v[148:149], v[188:189], v[148:149]
	v_cvt_pk_bf16_f32 v158, v185, v187
	v_pk_add_f32 v[148:149], v[190:191], v[148:149]
	v_cvt_pk_bf16_f32 v162, v184, v186
	v_pk_add_f32 v[148:149], v[192:193], v[148:149]
	v_cvt_pk_bf16_f32 v184, v143, v173
	v_pk_add_f32 v[148:149], v[194:195], v[148:149]
	v_cvt_pk_bf16_f32 v185, v189, v191
	v_pk_add_f32 v[148:149], v[196:197], v[148:149]
	v_cvt_pk_bf16_f32 v186, v193, v195
	v_pk_add_f32 v[148:149], v[198:199], v[148:149]
	v_cvt_pk_bf16_f32 v187, v197, v199
	v_pk_add_f32 v[120:121], v[120:121], v[148:149]
	v_cvt_pk_bf16_f32 v148, v142, v172
	v_cvt_pk_bf16_f32 v149, v188, v190
	v_cvt_pk_bf16_f32 v150, v192, v194
	v_cvt_pk_bf16_f32 v151, v196, v198
	s_waitcnt lgkmcnt(3)
	v_mfma_f32_16x16x32_bf16 v[34:37], v[164:167], v[156:159], v[34:37]
	s_waitcnt lgkmcnt(2)
	v_mfma_f32_16x16x32_bf16 v[38:41], v[168:171], v[156:159], v[38:41]
	s_waitcnt lgkmcnt(1)
	v_mfma_f32_16x16x32_bf16 v[42:45], v[176:179], v[156:159], v[42:45]
	s_waitcnt lgkmcnt(0)
	v_mfma_f32_16x16x32_bf16 v[46:49], v[180:183], v[156:159], v[46:49]
	v_mfma_f32_16x16x32_bf16 v[50:53], v[164:167], v[160:163], v[50:53]
	v_mfma_f32_16x16x32_bf16 v[54:57], v[168:171], v[160:163], v[54:57]
	v_mfma_f32_16x16x32_bf16 v[58:61], v[176:179], v[160:163], v[58:61]
	v_mfma_f32_16x16x32_bf16 v[62:65], v[180:183], v[160:163], v[62:65]
	v_mfma_f32_16x16x32_bf16 v[66:69], v[164:167], v[184:187], v[66:69]
	v_mfma_f32_16x16x32_bf16 v[70:73], v[168:171], v[184:187], v[70:73]
	v_mfma_f32_16x16x32_bf16 v[74:77], v[176:179], v[184:187], v[74:77]
	v_mfma_f32_16x16x32_bf16 v[78:81], v[180:183], v[184:187], v[78:81]
	v_mfma_f32_16x16x32_bf16 v[82:85], v[164:167], v[148:151], v[82:85]
	v_mfma_f32_16x16x32_bf16 v[86:89], v[168:171], v[148:151], v[86:89]
	v_mfma_f32_16x16x32_bf16 v[90:93], v[176:179], v[148:151], v[90:93]
	v_mfma_f32_16x16x32_bf16 v[94:97], v[180:183], v[148:151], v[94:97]
	s_mov_b32 s6, 1
	s_and_b64 vcc, exec, s[4:5]
	s_mov_b64 s[4:5], 0
	s_cbranch_vccnz .LBB0_3106

.LBB0_3123:
	s_lshl_b32 s17, s15, 5
	s_or_b32 s16, s17, s0
	s_cmp_gt_i32 s16, s10
	s_cselect_b64 s[18:19], -1, 0
	s_or_b32 s20, s16, 31
	s_cmp_lt_i32 s20, s3
	s_cselect_b64 s[20:21], -1, 0
	s_or_b64 s[18:19], s[18:19], s[20:21]
	s_and_b64 vcc, exec, s[18:19]
	s_cbranch_vccnz .LBB0_3122
	v_or_b32_e32 v131, s17, v208
	v_mad_u32_u24 v131, v131, s12, v124
	ds_read_b128 v[132:135], v131
	ds_read_b128 v[136:139], v131 offset:64
	ds_read_b128 v[140:143], v131 offset:2304
	ds_read_b128 v[148:151], v131 offset:2368
	v_lshl_add_u32 v131, s15, 6, v130
	ds_read_b128 v[152:155], v131 offset:9216
	ds_read_b128 v[156:159], v131 offset:11520
	ds_read_b128 v[160:163], v131 offset:13824
	ds_read_b128 v[164:167], v131 offset:16128
	v_add_u32_e32 v131, s16, v144
	v_sub_u32_e32 v168, v209, v131
	v_cvt_f32_i32_e32 v169, v168
	v_xad_u32 v170, v131, -1, v209
	v_cvt_f32_i32_e32 v171, v170
	v_cmp_gt_u32_e32 vcc, s13, v168
	v_or_b32_e32 v168, 2, v131
	v_sub_u32_e32 v168, v209, v168
	v_cndmask_b32_e32 v196, v1, v169, vcc
	v_cmp_gt_u32_e32 vcc, s13, v170
	v_cvt_f32_i32_e32 v169, v168
	v_or_b32_e32 v170, 3, v131
	v_sub_u32_e32 v170, v209, v170
	v_cndmask_b32_e32 v197, v1, v171, vcc
	v_cvt_f32_i32_e32 v171, v170
	v_cmp_gt_u32_e32 vcc, s13, v168
	v_or_b32_e32 v168, 4, v131
	v_sub_u32_e32 v168, v209, v168
	v_cndmask_b32_e32 v198, v1, v169, vcc
	v_cvt_f32_i32_e32 v169, v168
	v_cmp_gt_u32_e32 vcc, s13, v170
	v_or_b32_e32 v170, 5, v131
	v_sub_u32_e32 v170, v209, v170
	v_cndmask_b32_e32 v199, v1, v171, vcc
	v_cmp_gt_u32_e32 vcc, s13, v168
	v_or_b32_e32 v168, 6, v131
	v_cvt_f32_i32_e32 v171, v170
	v_sub_u32_e32 v168, v209, v168
	v_or_b32_e32 v131, 7, v131
	v_cndmask_b32_e32 v200, v1, v169, vcc
	v_cvt_f32_i32_e32 v169, v168
	v_sub_u32_e32 v131, v209, v131
	v_cmp_gt_u32_e32 vcc, s13, v170
	v_cvt_f32_i32_e32 v170, v131
	s_nop 0
	v_cndmask_b32_e32 v201, v1, v171, vcc
	v_cmp_gt_u32_e32 vcc, s13, v168
	s_nop 1
	v_cndmask_b32_e32 v202, v1, v169, vcc
	v_cmp_gt_u32_e32 vcc, s13, v131
	s_nop 1
	v_cndmask_b32_e32 v131, v1, v170, vcc
	s_waitcnt lgkmcnt(7)
	v_mfma_f32_16x16x32_bf16 v[168:171], v[132:135], v[2:5], 0
	v_mfma_f32_16x16x32_bf16 v[176:179], v[132:135], v[10:13], 0
	v_mfma_f32_16x16x32_bf16 v[184:187], v[132:135], v[18:21], 0
	v_mfma_f32_16x16x32_bf16 v[132:135], v[132:135], v[26:29], 0
	s_waitcnt lgkmcnt(6)
	v_mfma_f32_16x16x32_bf16 v[168:171], v[136:139], v[6:9], v[168:171]
	s_waitcnt lgkmcnt(5)
	v_mfma_f32_16x16x32_bf16 v[172:175], v[140:143], v[2:5], 0
	v_mfma_f32_16x16x32_bf16 v[176:179], v[136:139], v[14:17], v[176:179]
	v_mfma_f32_16x16x32_bf16 v[180:183], v[140:143], v[10:13], 0
	v_mfma_f32_16x16x32_bf16 v[184:187], v[136:139], v[22:25], v[184:187]
	v_mfma_f32_16x16x32_bf16 v[188:191], v[140:143], v[18:21], 0
	v_mfma_f32_16x16x32_bf16 v[132:135], v[136:139], v[30:33], v[132:135]
	v_mfma_f32_16x16x32_bf16 v[136:139], v[140:143], v[26:29], 0
	s_waitcnt lgkmcnt(4)
	v_mfma_f32_16x16x32_bf16 v[172:175], v[148:151], v[6:9], v[172:175]
	v_mfma_f32_16x16x32_bf16 v[180:183], v[148:151], v[14:17], v[180:183]
	v_mfma_f32_16x16x32_bf16 v[188:191], v[148:151], v[22:25], v[188:191]
	v_mfma_f32_16x16x32_bf16 v[136:139], v[148:151], v[30:33], v[136:139]
	v_fma_f32 v140, -v215, v196, v168
	v_fma_f32 v148, -v216, v196, v176
	v_exp_f32_e32 v149, v140
	v_fma_f32 v140, -v215, v197, v169
	v_exp_f32_e32 v148, v148
	v_fma_f32 v150, -v216, v197, v177
	v_exp_f32_e32 v151, v140
	v_fma_f32 v140, -v215, v198, v170
	v_exp_f32_e32 v150, v150
	v_fma_f32 v168, -v216, v198, v178
	v_exp_f32_e32 v169, v140
	v_fma_f32 v140, -v215, v199, v171
	v_exp_f32_e32 v168, v168
	v_fma_f32 v170, -v216, v199, v179
	v_exp_f32_e32 v171, v140
	v_fma_f32 v140, -v215, v200, v172
	v_exp_f32_e32 v170, v170
	v_fma_f32 v172, -v216, v200, v180
	v_exp_f32_e32 v193, v140
	v_fma_f32 v140, -v215, v201, v173
	v_exp_f32_e32 v192, v172
	v_fma_f32 v172, -v216, v201, v181
	v_pk_add_f32 v[176:177], v[148:149], 0 op_sel_hi:[1,0]
	v_exp_f32_e32 v173, v140
	v_fma_f32 v140, -v215, v202, v174
	v_exp_f32_e32 v172, v172
	v_fma_f32 v174, -v216, v202, v182
	v_pk_add_f32 v[176:177], v[150:151], v[176:177]
	v_exp_f32_e32 v195, v140
	v_fma_f32 v140, -v215, v131, v175
	v_exp_f32_e32 v194, v174
	v_fma_f32 v174, -v216, v131, v183
	v_pk_add_f32 v[176:177], v[168:169], v[176:177]
	v_exp_f32_e32 v175, v140
	v_exp_f32_e32 v174, v174
	v_pk_add_f32 v[176:177], v[170:171], v[176:177]
	v_fma_f32 v132, -v218, v196, v132
	v_pk_add_f32 v[176:177], v[192:193], v[176:177]
	v_cvt_pk_bf16_f32 v148, v148, v150
	v_pk_add_f32 v[176:177], v[172:173], v[176:177]
	v_cvt_pk_bf16_f32 v150, v192, v172
	v_pk_add_f32 v[176:177], v[194:195], v[176:177]
	v_exp_f32_e32 v172, v132
	v_fma_f32 v132, -v218, v197, v133
	v_cvt_pk_bf16_f32 v140, v149, v151
	v_pk_add_f32 v[176:177], v[174:175], v[176:177]
	v_cvt_pk_bf16_f32 v149, v168, v170
	v_cvt_pk_bf16_f32 v151, v194, v174
	v_fma_f32 v168, -v217, v196, v184
	v_exp_f32_e32 v174, v132
	v_fma_f32 v132, -v218, v198, v134
	v_cvt_pk_bf16_f32 v142, v193, v173
	v_pk_add_f32 v[122:123], v[122:123], v[176:177]
	v_exp_f32_e32 v173, v168
	v_fma_f32 v168, -v217, v197, v185
	v_exp_f32_e32 v176, v132
	v_fma_f32 v132, -v218, v199, v135
	v_cvt_pk_bf16_f32 v143, v195, v175
	v_exp_f32_e32 v175, v168
	v_fma_f32 v168, -v217, v198, v186
	v_exp_f32_e32 v178, v132
	v_fma_f32 v132, -v218, v200, v136
	v_exp_f32_e32 v177, v168
	v_fma_f32 v168, -v217, v199, v187
	v_exp_f32_e32 v180, v132
	v_fma_f32 v132, -v218, v201, v137
	v_exp_f32_e32 v179, v168
	v_fma_f32 v168, -v217, v200, v188
	v_exp_f32_e32 v182, v132
	v_fma_f32 v132, -v218, v202, v138
	v_exp_f32_e32 v181, v168
	v_fma_f32 v168, -v217, v201, v189
	v_exp_f32_e32 v184, v132
	v_pk_add_f32 v[132:133], v[172:173], 0 op_sel_hi:[1,0]
	v_exp_f32_e32 v183, v168
	v_fma_f32 v168, -v217, v202, v190
	v_pk_add_f32 v[132:133], v[174:175], v[132:133]
	v_exp_f32_e32 v185, v168
	v_fma_f32 v168, -v217, v131, v191
	v_fma_f32 v131, -v218, v131, v139
	v_pk_add_f32 v[132:133], v[176:177], v[132:133]
	v_exp_f32_e32 v187, v168
	v_exp_f32_e32 v186, v131
	v_pk_add_f32 v[132:133], v[178:179], v[132:133]
	v_cvt_pk_bf16_f32 v141, v169, v171
	v_pk_add_f32 v[132:133], v[180:181], v[132:133]
	v_cvt_pk_bf16_f32 v168, v173, v175
	v_pk_add_f32 v[132:133], v[182:183], v[132:133]
	v_cvt_pk_bf16_f32 v169, v177, v179
	v_pk_add_f32 v[132:133], v[184:185], v[132:133]
	v_cvt_pk_bf16_f32 v170, v181, v183
	v_pk_add_f32 v[132:133], v[186:187], v[132:133]
	v_cvt_pk_bf16_f32 v171, v185, v187
	v_pk_add_f32 v[120:121], v[120:121], v[132:133]
	v_cvt_pk_bf16_f32 v132, v172, v174
	v_cvt_pk_bf16_f32 v133, v176, v178
	v_cvt_pk_bf16_f32 v134, v180, v182
	v_cvt_pk_bf16_f32 v135, v184, v186
	s_waitcnt lgkmcnt(3)
	v_mfma_f32_16x16x32_bf16 v[94:97], v[152:155], v[140:143], v[94:97]
	s_waitcnt lgkmcnt(2)
	v_mfma_f32_16x16x32_bf16 v[90:93], v[156:159], v[140:143], v[90:93]
	s_waitcnt lgkmcnt(1)
	v_mfma_f32_16x16x32_bf16 v[86:89], v[160:163], v[140:143], v[86:89]
	s_waitcnt lgkmcnt(0)
	v_mfma_f32_16x16x32_bf16 v[82:85], v[164:167], v[140:143], v[82:85]
	v_mfma_f32_16x16x32_bf16 v[78:81], v[152:155], v[148:151], v[78:81]
	v_mfma_f32_16x16x32_bf16 v[74:77], v[156:159], v[148:151], v[74:77]
	v_mfma_f32_16x16x32_bf16 v[70:73], v[160:163], v[148:151], v[70:73]
	v_mfma_f32_16x16x32_bf16 v[66:69], v[164:167], v[148:151], v[66:69]
	v_mfma_f32_16x16x32_bf16 v[62:65], v[152:155], v[168:171], v[62:65]
	v_mfma_f32_16x16x32_bf16 v[58:61], v[156:159], v[168:171], v[58:61]
	v_mfma_f32_16x16x32_bf16 v[54:57], v[160:163], v[168:171], v[54:57]
	v_mfma_f32_16x16x32_bf16 v[50:53], v[164:167], v[168:171], v[50:53]
	v_mfma_f32_16x16x32_bf16 v[46:49], v[152:155], v[132:135], v[46:49]
	v_mfma_f32_16x16x32_bf16 v[42:45], v[156:159], v[132:135], v[42:45]
	v_mfma_f32_16x16x32_bf16 v[38:41], v[160:163], v[132:135], v[38:41]
	v_mfma_f32_16x16x32_bf16 v[34:37], v[164:167], v[132:135], v[34:37]
	s_branch .LBB0_3122
